# gemm256 K-loop: staged pieces retired one per phase (vmcnt 10 in phases 4,5,6,8,1,2) instead of a whole buffer at vmcnt 6
# speedup vs baseline: 1.1325x; 1.0040x over previous
; #define STAGE_A(Pp, br, kt) { const char* g_ = (const char*)(A + (size_t)(br) * lda + (size_t)(kt) * BK); \
;     __builtin_amdgcn_global_load_lds((const unsigned*)(g_ + oa0), (LAS unsigned*)((Pp) + tid * 16), 16, 0, 0); \
;     __builtin_amdgcn_global_load_lds((const unsigned*)(g_ + oa1), (LAS unsigned*)((Pp) + tid * 16 + 8192), 16, 0, 0); }
; #define STAGE_B(Pp, br, kt) { const char* g_ = (const char*)(Bt + (size_t)(br) * ldb + (size_t)(kt) * BK); \
;     __builtin_amdgcn_global_load_lds((const unsigned*)(g_ + ob0), (LAS unsigned*)((Pp) + tid * 16), 16, 0, 0); \
;     __builtin_amdgcn_global_load_lds((const unsigned*)(g_ + ob1), (LAS unsigned*)((Pp) + tid * 16 + 8192), 16, 0, 0); }
; #define LDA8(dst, b, h) _Pragma("unroll") for (int m = 0; m < 4; ++m) _Pragma("unroll") for (int k = 0; k < 2; ++k) \
;     dst[m][k] = *(const bf16x8*)(lrda + ((b) * 2 + (h)) * HTB + (2 * m + k) * 1024)
; #define LDB8(dst, b, h) _Pragma("unroll") for (int n = 0; n < 2; ++n) _Pragma("unroll") for (int k = 0; k < 2; ++k) \
;     dst[n][k] = *(const bf16x8*)(lrdb + ((b) * 2 + (h)) * HTB + (2 * n + k) * 1024)
; #define MMA8(ai, bj, AT, BT) { __builtin_amdgcn_s_setprio(1); \
;     _Pragma("unroll") for (int m = 0; m < 4; ++m) _Pragma("unroll") for (int n = 0; n < 2; ++n) _Pragma("unroll") for (int k = 0; k < 2; ++k) \
;       acc[ai][bj][m][n] = __builtin_amdgcn_mfma_f32_16x16x32_bf16(AT[m][k], BT[n][k], acc[ai][bj][m][n], 0, 0, 0); \
;     __builtin_amdgcn_s_setprio(0); }
; #define WAIT_V(n) asm volatile("s_waitcnt vmcnt(" #n ")" ::: "memory")
; template <class Epi>
; DI void gemm256(const bf16_t* __restrict__ A, int lda, const bf16_t* __restrict__ Bt, int ldb, int K, char* lds, Epi epi) {
;     ...
;   for (int t = 0; t < nt - 2; t += 2) {
;     LDB8(B0, 0, 0); SCHED8; LDA8(At, 0, 0); STAGE_A(SA8(1, 1), HALFR, t + 1);
;     WAIT_L(8); BAR8; WAIT_L(0); MMA8(0, 0, At, B0); BAR8; SCHED8;
;     LDB8(B1, 0, 1); STAGE_B(SB8(0, 0), 0, t + 2);
;     BAR8; WAIT_L(0); MMA8(0, 1, At, B1); BAR8;
;     LDA8(At, 0, 1); STAGE_A(SA8(0, 0), 0, t + 2);
;     BAR8; WAIT_L(0); MMA8(1, 0, At, B0); BAR8; SCHED8;
;     STAGE_B(SB8(0, 1), HALFR, t + 2);
;     WAIT_V(6); BAR8; MMA8(1, 1, At, B1); BAR8;
;     LDB8(B0, 1, 0); SCHED8; LDA8(At, 1, 0); STAGE_A(SA8(0, 1), HALFR, t + 2);
;     WAIT_L(8); BAR8; WAIT_L(0); MMA8(0, 0, At, B0); BAR8; SCHED8;
;     LDB8(B1, 1, 1); STAGE_B(SB8(1, 0), 0, t + 3);
.LBB0_318:
	ds_read_b128 v[164:167], v147
	ds_read_b128 v[168:171], v147 offset:1024
	ds_read_b128 v[172:175], v147 offset:2048
	ds_read_b128 v[176:179], v147 offset:3072
	v_add_u32_e32 v162, 0xc000, v150
	v_lshl_add_u64 v[184:185], s[36:37], 0, v[134:135]
	v_readfirstlane_b32 s18, v162
	v_add_u32_e32 v163, 0xe000, v150
	v_lshl_add_u64 v[236:237], v[184:185], 0, s[38:39]
	s_mov_b32 m0, s18
	v_lshl_add_u64 v[214:215], s[36:37], 0, v[132:133]
	v_readfirstlane_b32 s18, v163
	ds_read_b128 v[180:183], v146
	ds_read_b128 v[188:191], v146 offset:1024
	ds_read_b128 v[192:195], v146 offset:2048
	ds_read_b128 v[216:219], v146 offset:3072
	ds_read_b128 v[220:223], v146 offset:4096
	ds_read_b128 v[224:227], v146 offset:5120
	ds_read_b128 v[228:231], v146 offset:6144
	ds_read_b128 v[232:235], v146 offset:7168
	global_load_lds_dwordx4 v[236:237], off
	v_lshl_add_u64 v[236:237], v[214:215], 0, s[38:39]
	s_mov_b32 m0, s18
	s_nop 0
	global_load_lds_dwordx4 v[236:237], off
	s_waitcnt lgkmcnt(8)
	s_waitcnt vmcnt(10)
	s_barrier
	s_waitcnt lgkmcnt(0)
	s_setprio 1
	s_waitcnt lgkmcnt(0)
	v_mfma_f32_16x16x32_bf16 v[126:129], v[180:183], v[164:167], v[126:129]
	v_mfma_f32_16x16x32_bf16 v[122:125], v[180:183], v[172:175], v[122:125]
	v_mfma_f32_16x16x32_bf16 v[118:121], v[192:195], v[164:167], v[118:121]
	v_mfma_f32_16x16x32_bf16 v[114:117], v[192:195], v[172:175], v[114:117]
	v_mfma_f32_16x16x32_bf16 v[110:113], v[220:223], v[164:167], v[110:113]
	v_mfma_f32_16x16x32_bf16 v[106:109], v[220:223], v[172:175], v[106:109]
	v_mfma_f32_16x16x32_bf16 v[102:105], v[228:231], v[164:167], v[102:105]
	v_mfma_f32_16x16x32_bf16 v[98:101], v[228:231], v[172:175], v[98:101]
	v_mfma_f32_16x16x32_bf16 v[126:129], v[188:191], v[168:171], v[126:129]
	v_mfma_f32_16x16x32_bf16 v[122:125], v[188:191], v[176:179], v[122:125]
	v_mfma_f32_16x16x32_bf16 v[118:121], v[216:219], v[168:171], v[118:121]
	v_mfma_f32_16x16x32_bf16 v[114:117], v[216:219], v[176:179], v[114:117]
	v_mfma_f32_16x16x32_bf16 v[110:113], v[224:227], v[168:171], v[110:113]
	v_mfma_f32_16x16x32_bf16 v[106:109], v[224:227], v[176:179], v[106:109]
	v_mfma_f32_16x16x32_bf16 v[102:105], v[232:235], v[168:171], v[102:105]
	v_mfma_f32_16x16x32_bf16 v[98:101], v[232:235], v[176:179], v[98:101]
	s_setprio 0
	s_barrier
	v_lshl_add_u64 v[202:203], s[36:37], 0, v[138:139]
	v_readfirstlane_b32 s18, v148
	v_lshl_add_u64 v[212:213], v[202:203], 0, s[20:21]
	s_mov_b32 m0, s18
	ds_read_b128 v[236:239], v147 offset:16384
	ds_read_b128 v[240:243], v147 offset:17408
	ds_read_b128 v[244:247], v147 offset:18432
	ds_read_b128 v[248:251], v147 offset:19456
	global_load_lds_dwordx4 v[212:213], off
	v_lshl_add_u64 v[212:213], s[36:37], 0, v[136:137]
	v_readfirstlane_b32 s18, v149
	v_lshl_add_u64 v[210:211], v[212:213], 0, s[20:21]
	s_mov_b32 m0, s18
	s_nop 0
	global_load_lds_dwordx4 v[210:211], off
	s_waitcnt vmcnt(10)
	s_barrier
	s_waitcnt lgkmcnt(0)
	s_setprio 1
	s_waitcnt lgkmcnt(0)
	v_mfma_f32_16x16x32_bf16 v[94:97], v[180:183], v[236:239], v[94:97]
	v_mfma_f32_16x16x32_bf16 v[90:93], v[180:183], v[244:247], v[90:93]
	v_mfma_f32_16x16x32_bf16 v[86:89], v[192:195], v[236:239], v[86:89]
	v_mfma_f32_16x16x32_bf16 v[82:85], v[192:195], v[244:247], v[82:85]
	v_mfma_f32_16x16x32_bf16 v[78:81], v[220:223], v[236:239], v[78:81]
	v_mfma_f32_16x16x32_bf16 v[74:77], v[220:223], v[244:247], v[74:77]
	v_mfma_f32_16x16x32_bf16 v[70:73], v[228:231], v[236:239], v[70:73]
	v_mfma_f32_16x16x32_bf16 v[66:69], v[228:231], v[244:247], v[66:69]
	v_mfma_f32_16x16x32_bf16 v[94:97], v[188:191], v[240:243], v[94:97]
	v_mfma_f32_16x16x32_bf16 v[90:93], v[188:191], v[248:251], v[90:93]
	v_mfma_f32_16x16x32_bf16 v[86:89], v[216:219], v[240:243], v[86:89]
	v_mfma_f32_16x16x32_bf16 v[82:85], v[216:219], v[248:251], v[82:85]
	v_mfma_f32_16x16x32_bf16 v[78:81], v[224:227], v[240:243], v[78:81]
	v_mfma_f32_16x16x32_bf16 v[74:77], v[224:227], v[248:251], v[74:77]
	v_mfma_f32_16x16x32_bf16 v[70:73], v[232:235], v[240:243], v[70:73]
	v_mfma_f32_16x16x32_bf16 v[66:69], v[232:235], v[248:251], v[66:69]
	s_setprio 0
	v_readfirstlane_b32 s18, v150
	v_lshl_add_u64 v[210:211], v[184:185], 0, s[66:67]
	s_mov_b32 m0, s18
	v_readfirstlane_b32 s18, v151
	s_barrier
	ds_read_b128 v[180:183], v146 offset:16384
	ds_read_b128 v[188:191], v146 offset:17408
	ds_read_b128 v[192:195], v146 offset:18432
	ds_read_b128 v[216:219], v146 offset:19456
	ds_read_b128 v[220:223], v146 offset:20480
	ds_read_b128 v[224:227], v146 offset:21504
	ds_read_b128 v[228:231], v146 offset:22528
	ds_read_b128 v[232:235], v146 offset:23552
	global_load_lds_dwordx4 v[210:211], off
	v_lshl_add_u64 v[210:211], v[214:215], 0, s[66:67]
	s_mov_b32 m0, s18
	s_nop 0
	global_load_lds_dwordx4 v[210:211], off
	s_barrier
	s_waitcnt lgkmcnt(0)
	s_setprio 1
	s_waitcnt lgkmcnt(0)
	v_mfma_f32_16x16x32_bf16 v[62:65], v[180:183], v[164:167], v[62:65]
	v_mfma_f32_16x16x32_bf16 v[58:61], v[180:183], v[172:175], v[58:61]
	v_mfma_f32_16x16x32_bf16 v[54:57], v[192:195], v[164:167], v[54:57]
	v_mfma_f32_16x16x32_bf16 v[50:53], v[192:195], v[172:175], v[50:53]
	v_mfma_f32_16x16x32_bf16 v[46:49], v[220:223], v[164:167], v[46:49]
	v_mfma_f32_16x16x32_bf16 v[42:45], v[220:223], v[172:175], v[42:45]
	v_mfma_f32_16x16x32_bf16 v[38:41], v[228:231], v[164:167], v[38:41]
	v_mfma_f32_16x16x32_bf16 v[34:37], v[228:231], v[172:175], v[34:37]
	v_mfma_f32_16x16x32_bf16 v[62:65], v[188:191], v[168:171], v[62:65]
	v_mfma_f32_16x16x32_bf16 v[58:61], v[188:191], v[176:179], v[58:61]
	v_mfma_f32_16x16x32_bf16 v[54:57], v[216:219], v[168:171], v[54:57]
	v_mfma_f32_16x16x32_bf16 v[50:53], v[216:219], v[176:179], v[50:53]
	v_mfma_f32_16x16x32_bf16 v[46:49], v[224:227], v[168:171], v[46:49]
	v_mfma_f32_16x16x32_bf16 v[42:45], v[224:227], v[176:179], v[42:45]
	v_mfma_f32_16x16x32_bf16 v[38:41], v[232:235], v[168:171], v[38:41]
	v_mfma_f32_16x16x32_bf16 v[34:37], v[232:235], v[176:179], v[34:37]
	s_setprio 0
	s_barrier
; #define STAGE_A(Pp, br, kt) { const char* g_ = (const char*)(A + (size_t)(br) * lda + (size_t)(kt) * BK); \
;     __builtin_amdgcn_global_load_lds((const unsigned*)(g_ + oa0), (LAS unsigned*)((Pp) + tid * 16), 16, 0, 0); \
;     __builtin_amdgcn_global_load_lds((const unsigned*)(g_ + oa1), (LAS unsigned*)((Pp) + tid * 16 + 8192), 16, 0, 0); }
; #define STAGE_B(Pp, br, kt) { const char* g_ = (const char*)(Bt + (size_t)(br) * ldb + (size_t)(kt) * BK); \
;     __builtin_amdgcn_global_load_lds((const unsigned*)(g_ + ob0), (LAS unsigned*)((Pp) + tid * 16), 16, 0, 0); \
;     __builtin_amdgcn_global_load_lds((const unsigned*)(g_ + ob1), (LAS unsigned*)((Pp) + tid * 16 + 8192), 16, 0, 0); }
; #define LDA8(dst, b, h) _Pragma("unroll") for (int m = 0; m < 4; ++m) _Pragma("unroll") for (int k = 0; k < 2; ++k) \
;     dst[m][k] = *(const bf16x8*)(lrda + ((b) * 2 + (h)) * HTB + (2 * m + k) * 1024)
; #define LDB8(dst, b, h) _Pragma("unroll") for (int n = 0; n < 2; ++n) _Pragma("unroll") for (int k = 0; k < 2; ++k) \
;     dst[n][k] = *(const bf16x8*)(lrdb + ((b) * 2 + (h)) * HTB + (2 * n + k) * 1024)
; #define MMA8(ai, bj, AT, BT) { __builtin_amdgcn_s_setprio(1); \
;     _Pragma("unroll") for (int m = 0; m < 4; ++m) _Pragma("unroll") for (int n = 0; n < 2; ++n) _Pragma("unroll") for (int k = 0; k < 2; ++k) \
;       acc[ai][bj][m][n] = __builtin_amdgcn_mfma_f32_16x16x32_bf16(AT[m][k], BT[n][k], acc[ai][bj][m][n], 0, 0, 0); \
;     __builtin_amdgcn_s_setprio(0); }
; #define WAIT_V(n) asm volatile("s_waitcnt vmcnt(" #n ")" ::: "memory")
; #define WAIT_L(n) asm volatile("s_waitcnt lgkmcnt(" #n ")" ::: "memory")
; #define BAR8 __builtin_amdgcn_s_barrier()
; #define SCHED8 __builtin_amdgcn_sched_barrier(0)
; template <class Epi>
; DI void gemm256(const bf16_t* __restrict__ A, int lda, const bf16_t* __restrict__ Bt, int ldb, int K, char* lds, Epi epi) {
;     ...
;     WAIT_V(6); BAR8; MMA8(1, 1, At, B1); BAR8;
;     LDB8(B0, 1, 0); SCHED8; LDA8(At, 1, 0); STAGE_A(SA8(0, 1), HALFR, t + 2);
;     WAIT_L(8); BAR8; WAIT_L(0); MMA8(0, 0, At, B0); BAR8; SCHED8;
;     LDB8(B1, 1, 1); STAGE_B(SB8(1, 0), 0, t + 3);
;     BAR8; WAIT_L(0); MMA8(0, 1, At, B1); BAR8;
;     LDA8(At, 1, 1); STAGE_A(SA8(1, 0), 0, t + 3);
;     BAR8; WAIT_L(0); MMA8(1, 0, At, B0); BAR8; SCHED8;
	v_readfirstlane_b32 s18, v152
	v_lshl_add_u64 v[164:165], v[202:203], 0, s[34:35]
	s_mov_b32 m0, s18
	v_readfirstlane_b32 s18, v153
	global_load_lds_dwordx4 v[164:165], off
	v_lshl_add_u64 v[164:165], v[212:213], 0, s[34:35]
	s_mov_b32 m0, s18
	s_nop 0
	global_load_lds_dwordx4 v[164:165], off
	s_waitcnt vmcnt(10)
	s_barrier
	s_setprio 1
	v_mfma_f32_16x16x32_bf16 v[30:33], v[180:183], v[236:239], v[30:33]
	v_mfma_f32_16x16x32_bf16 v[26:29], v[180:183], v[244:247], v[26:29]
	v_mfma_f32_16x16x32_bf16 v[22:25], v[192:195], v[236:239], v[22:25]
	v_mfma_f32_16x16x32_bf16 v[18:21], v[192:195], v[244:247], v[18:21]
	v_mfma_f32_16x16x32_bf16 v[14:17], v[220:223], v[236:239], v[14:17]
	v_mfma_f32_16x16x32_bf16 v[10:13], v[220:223], v[244:247], v[10:13]
	v_mfma_f32_16x16x32_bf16 v[6:9], v[228:231], v[236:239], v[6:9]
	v_mfma_f32_16x16x32_bf16 v[2:5], v[228:231], v[244:247], v[2:5]
	v_mfma_f32_16x16x32_bf16 v[30:33], v[188:191], v[240:243], v[30:33]
	v_mfma_f32_16x16x32_bf16 v[26:29], v[188:191], v[248:251], v[26:29]
	v_mfma_f32_16x16x32_bf16 v[22:25], v[216:219], v[240:243], v[22:25]
	v_mfma_f32_16x16x32_bf16 v[18:21], v[216:219], v[248:251], v[18:21]
	v_mfma_f32_16x16x32_bf16 v[14:17], v[224:227], v[240:243], v[14:17]
	v_mfma_f32_16x16x32_bf16 v[10:13], v[224:227], v[248:251], v[10:13]
	v_mfma_f32_16x16x32_bf16 v[6:9], v[232:235], v[240:243], v[6:9]
	v_mfma_f32_16x16x32_bf16 v[2:5], v[232:235], v[248:251], v[2:5]
	s_setprio 0
	s_barrier
	ds_read_b128 v[164:167], v147 offset:32768
	ds_read_b128 v[168:171], v147 offset:33792
	ds_read_b128 v[172:175], v147 offset:34816
	ds_read_b128 v[176:179], v147 offset:35840
	v_readfirstlane_b32 s18, v154
	v_lshl_add_u64 v[210:211], v[184:185], 0, s[16:17]
	s_mov_b32 m0, s18
	v_readfirstlane_b32 s18, v155
	ds_read_b128 v[180:183], v146 offset:32768
	ds_read_b128 v[188:191], v146 offset:33792
	ds_read_b128 v[192:195], v146 offset:34816
	ds_read_b128 v[216:219], v146 offset:35840
	ds_read_b128 v[220:223], v146 offset:36864
	ds_read_b128 v[224:227], v146 offset:37888
	ds_read_b128 v[228:231], v146 offset:38912
	ds_read_b128 v[232:235], v146 offset:39936
	global_load_lds_dwordx4 v[210:211], off
	v_lshl_add_u64 v[210:211], v[214:215], 0, s[16:17]
	s_mov_b32 m0, s18
	s_nop 0
	global_load_lds_dwordx4 v[210:211], off
	s_waitcnt lgkmcnt(8)
	s_waitcnt vmcnt(10)
	s_barrier
	s_waitcnt lgkmcnt(0)
	s_setprio 1
	s_waitcnt lgkmcnt(0)
	v_mfma_f32_16x16x32_bf16 v[126:129], v[180:183], v[164:167], v[126:129]
	v_mfma_f32_16x16x32_bf16 v[122:125], v[180:183], v[172:175], v[122:125]
	v_mfma_f32_16x16x32_bf16 v[118:121], v[192:195], v[164:167], v[118:121]
	v_mfma_f32_16x16x32_bf16 v[114:117], v[192:195], v[172:175], v[114:117]
	v_mfma_f32_16x16x32_bf16 v[110:113], v[220:223], v[164:167], v[110:113]
	v_mfma_f32_16x16x32_bf16 v[106:109], v[220:223], v[172:175], v[106:109]
	v_mfma_f32_16x16x32_bf16 v[102:105], v[228:231], v[164:167], v[102:105]
	v_mfma_f32_16x16x32_bf16 v[98:101], v[228:231], v[172:175], v[98:101]
	v_mfma_f32_16x16x32_bf16 v[126:129], v[188:191], v[168:171], v[126:129]
	v_mfma_f32_16x16x32_bf16 v[122:125], v[188:191], v[176:179], v[122:125]
	v_mfma_f32_16x16x32_bf16 v[118:121], v[216:219], v[168:171], v[118:121]
	v_mfma_f32_16x16x32_bf16 v[114:117], v[216:219], v[176:179], v[114:117]
	v_mfma_f32_16x16x32_bf16 v[110:113], v[224:227], v[168:171], v[110:113]
	v_mfma_f32_16x16x32_bf16 v[106:109], v[224:227], v[176:179], v[106:109]
	v_mfma_f32_16x16x32_bf16 v[102:105], v[232:235], v[168:171], v[102:105]
	v_mfma_f32_16x16x32_bf16 v[98:101], v[232:235], v[176:179], v[98:101]
	s_setprio 0
	s_barrier
	v_readfirstlane_b32 s18, v156
	v_lshl_add_u64 v[210:211], v[202:203], 0, s[48:49]
	s_mov_b32 m0, s18
	v_readfirstlane_b32 s18, v157
	ds_read_b128 v[236:239], v147 offset:49152
	ds_read_b128 v[240:243], v147 offset:50176
	ds_read_b128 v[244:247], v147 offset:51200
	ds_read_b128 v[248:251], v147 offset:52224
	global_load_lds_dwordx4 v[210:211], off
	v_lshl_add_u64 v[210:211], v[212:213], 0, s[48:49]
	s_mov_b32 m0, s18
	s_nop 0
	global_load_lds_dwordx4 v[210:211], off
	s_waitcnt vmcnt(10)
	s_barrier
	s_waitcnt lgkmcnt(0)
	s_setprio 1
	s_waitcnt lgkmcnt(0)
	v_mfma_f32_16x16x32_bf16 v[94:97], v[180:183], v[236:239], v[94:97]
	v_mfma_f32_16x16x32_bf16 v[90:93], v[180:183], v[244:247], v[90:93]
	v_mfma_f32_16x16x32_bf16 v[86:89], v[192:195], v[236:239], v[86:89]
	v_mfma_f32_16x16x32_bf16 v[82:85], v[192:195], v[244:247], v[82:85]
	v_mfma_f32_16x16x32_bf16 v[78:81], v[220:223], v[236:239], v[78:81]
	v_mfma_f32_16x16x32_bf16 v[74:77], v[220:223], v[244:247], v[74:77]
	v_mfma_f32_16x16x32_bf16 v[70:73], v[228:231], v[236:239], v[70:73]
	v_mfma_f32_16x16x32_bf16 v[66:69], v[228:231], v[244:247], v[66:69]
	v_mfma_f32_16x16x32_bf16 v[94:97], v[188:191], v[240:243], v[94:97]
	v_mfma_f32_16x16x32_bf16 v[90:93], v[188:191], v[248:251], v[90:93]
	v_mfma_f32_16x16x32_bf16 v[86:89], v[216:219], v[240:243], v[86:89]
	v_mfma_f32_16x16x32_bf16 v[82:85], v[216:219], v[248:251], v[82:85]
	v_mfma_f32_16x16x32_bf16 v[78:81], v[224:227], v[240:243], v[78:81]
	v_mfma_f32_16x16x32_bf16 v[74:77], v[224:227], v[248:251], v[74:77]
	v_mfma_f32_16x16x32_bf16 v[70:73], v[232:235], v[240:243], v[70:73]
	v_mfma_f32_16x16x32_bf16 v[66:69], v[232:235], v[248:251], v[66:69]
	s_setprio 0
	v_readfirstlane_b32 s18, v158
	v_lshl_add_u64 v[184:185], v[184:185], 0, s[70:71]
	s_mov_b32 m0, s18
	v_readfirstlane_b32 s18, v159
	s_barrier
; #define STAGE_A(Pp, br, kt) { const char* g_ = (const char*)(A + (size_t)(br) * lda + (size_t)(kt) * BK); \
;     __builtin_amdgcn_global_load_lds((const unsigned*)(g_ + oa0), (LAS unsigned*)((Pp) + tid * 16), 16, 0, 0); \
;     __builtin_amdgcn_global_load_lds((const unsigned*)(g_ + oa1), (LAS unsigned*)((Pp) + tid * 16 + 8192), 16, 0, 0); }
; #define STAGE_B(Pp, br, kt) { const char* g_ = (const char*)(Bt + (size_t)(br) * ldb + (size_t)(kt) * BK); \
;     __builtin_amdgcn_global_load_lds((const unsigned*)(g_ + ob0), (LAS unsigned*)((Pp) + tid * 16), 16, 0, 0); \
;     __builtin_amdgcn_global_load_lds((const unsigned*)(g_ + ob1), (LAS unsigned*)((Pp) + tid * 16 + 8192), 16, 0, 0); }
; #define LDA8(dst, b, h) _Pragma("unroll") for (int m = 0; m < 4; ++m) _Pragma("unroll") for (int k = 0; k < 2; ++k) \
;     dst[m][k] = *(const bf16x8*)(lrda + ((b) * 2 + (h)) * HTB + (2 * m + k) * 1024)
; #define LDB8(dst, b, h) _Pragma("unroll") for (int n = 0; n < 2; ++n) _Pragma("unroll") for (int k = 0; k < 2; ++k) \
;     dst[n][k] = *(const bf16x8*)(lrdb + ((b) * 2 + (h)) * HTB + (2 * n + k) * 1024)
; #define MMA8(ai, bj, AT, BT) { __builtin_amdgcn_s_setprio(1); \
;     _Pragma("unroll") for (int m = 0; m < 4; ++m) _Pragma("unroll") for (int n = 0; n < 2; ++n) _Pragma("unroll") for (int k = 0; k < 2; ++k) \
;       acc[ai][bj][m][n] = __builtin_amdgcn_mfma_f32_16x16x32_bf16(AT[m][k], BT[n][k], acc[ai][bj][m][n], 0, 0, 0); \
;     __builtin_amdgcn_s_setprio(0); }
; #define WAIT_V(n) asm volatile("s_waitcnt vmcnt(" #n ")" ::: "memory")
; #define WAIT_L(n) asm volatile("s_waitcnt lgkmcnt(" #n ")" ::: "memory")
; #define BAR8 __builtin_amdgcn_s_barrier()
; #define SCHED8 __builtin_amdgcn_sched_barrier(0)
; template <class Epi>
; DI void gemm256(const bf16_t* __restrict__ A, int lda, const bf16_t* __restrict__ Bt, int ldb, int K, char* lds, Epi epi) {
;     ...
;     LDA8(At, 1, 1); STAGE_A(SA8(1, 0), 0, t + 3);
;     BAR8; WAIT_L(0); MMA8(1, 0, At, B0); BAR8; SCHED8;
;     STAGE_B(SB8(1, 1), HALFR, t + 3);
;     WAIT_V(6); BAR8; MMA8(1, 1, At, B1); BAR8;
;   }
;   { LDB8(B0, 0, 0); LDA8(At, 0, 0); STAGE_A(SA8(1, 1), HALFR, nt - 1);
	ds_read_b128 v[180:183], v146 offset:49152
	ds_read_b128 v[188:191], v146 offset:50176
	ds_read_b128 v[192:195], v146 offset:51200
	ds_read_b128 v[216:219], v146 offset:52224
	ds_read_b128 v[220:223], v146 offset:53248
	ds_read_b128 v[224:227], v146 offset:54272
	ds_read_b128 v[228:231], v146 offset:55296
	ds_read_b128 v[232:235], v146 offset:56320
	global_load_lds_dwordx4 v[184:185], off
	v_lshl_add_u64 v[184:185], v[214:215], 0, s[70:71]
	s_mov_b32 m0, s18
	s_nop 0
	global_load_lds_dwordx4 v[184:185], off
	s_barrier
	s_waitcnt lgkmcnt(0)
	s_setprio 1
	s_waitcnt lgkmcnt(0)
	v_mfma_f32_16x16x32_bf16 v[62:65], v[180:183], v[164:167], v[62:65]
	v_mfma_f32_16x16x32_bf16 v[58:61], v[180:183], v[172:175], v[58:61]
	v_mfma_f32_16x16x32_bf16 v[54:57], v[192:195], v[164:167], v[54:57]
	v_mfma_f32_16x16x32_bf16 v[50:53], v[192:195], v[172:175], v[50:53]
	v_mfma_f32_16x16x32_bf16 v[46:49], v[220:223], v[164:167], v[46:49]
	v_mfma_f32_16x16x32_bf16 v[42:45], v[220:223], v[172:175], v[42:45]
	v_mfma_f32_16x16x32_bf16 v[38:41], v[228:231], v[164:167], v[38:41]
	v_mfma_f32_16x16x32_bf16 v[34:37], v[228:231], v[172:175], v[34:37]
	v_mfma_f32_16x16x32_bf16 v[62:65], v[188:191], v[168:171], v[62:65]
	v_mfma_f32_16x16x32_bf16 v[58:61], v[188:191], v[176:179], v[58:61]
	v_mfma_f32_16x16x32_bf16 v[54:57], v[216:219], v[168:171], v[54:57]
	v_mfma_f32_16x16x32_bf16 v[50:53], v[216:219], v[176:179], v[50:53]
	v_mfma_f32_16x16x32_bf16 v[46:49], v[224:227], v[168:171], v[46:49]
	v_mfma_f32_16x16x32_bf16 v[42:45], v[224:227], v[176:179], v[42:45]
	v_mfma_f32_16x16x32_bf16 v[38:41], v[232:235], v[168:171], v[38:41]
	v_mfma_f32_16x16x32_bf16 v[34:37], v[232:235], v[176:179], v[34:37]
	s_setprio 0
	s_barrier
	v_readfirstlane_b32 s18, v160
	v_lshl_add_u64 v[164:165], v[202:203], 0, s[64:65]
	s_mov_b32 m0, s18
	v_readfirstlane_b32 s18, v161
	global_load_lds_dwordx4 v[164:165], off
	v_lshl_add_u64 v[164:165], v[212:213], 0, s[64:65]
	s_mov_b32 m0, s18
	s_nop 0
	global_load_lds_dwordx4 v[164:165], off
	s_waitcnt vmcnt(10)
	s_barrier
	s_setprio 1
	v_mfma_f32_16x16x32_bf16 v[30:33], v[180:183], v[236:239], v[30:33]
	v_mfma_f32_16x16x32_bf16 v[26:29], v[180:183], v[244:247], v[26:29]
	v_mfma_f32_16x16x32_bf16 v[22:25], v[192:195], v[236:239], v[22:25]
	v_mfma_f32_16x16x32_bf16 v[18:21], v[192:195], v[244:247], v[18:21]
	v_mfma_f32_16x16x32_bf16 v[14:17], v[220:223], v[236:239], v[14:17]
	v_mfma_f32_16x16x32_bf16 v[10:13], v[220:223], v[244:247], v[10:13]
	v_mfma_f32_16x16x32_bf16 v[6:9], v[228:231], v[236:239], v[6:9]
	v_mfma_f32_16x16x32_bf16 v[2:5], v[228:231], v[244:247], v[2:5]
	v_mfma_f32_16x16x32_bf16 v[30:33], v[188:191], v[240:243], v[30:33]
	v_mfma_f32_16x16x32_bf16 v[26:29], v[188:191], v[248:251], v[26:29]
	v_mfma_f32_16x16x32_bf16 v[22:25], v[216:219], v[240:243], v[22:25]
	v_mfma_f32_16x16x32_bf16 v[18:21], v[216:219], v[248:251], v[18:21]
	v_mfma_f32_16x16x32_bf16 v[14:17], v[224:227], v[240:243], v[14:17]
	v_mfma_f32_16x16x32_bf16 v[10:13], v[224:227], v[248:251], v[10:13]
	v_mfma_f32_16x16x32_bf16 v[6:9], v[232:235], v[240:243], v[6:9]
	v_mfma_f32_16x16x32_bf16 v[2:5], v[232:235], v[248:251], v[2:5]
	s_setprio 0
	s_add_i32 s5, s5, 2
	v_lshl_add_u64 v[132:133], v[132:133], 0, s[22:23]
	v_lshl_add_u64 v[134:135], v[134:135], 0, s[22:23]
	v_lshl_add_u64 v[136:137], v[136:137], 0, s[22:23]
	s_cmp_lt_u32 s5, 12
	v_lshl_add_u64 v[138:139], v[138:139], 0, s[22:23]
	s_barrier
	s_cbranch_scc1 .LBB0_318
	s_add_u32 s18, s46, 0x40780
	s_addc_u32 s19, s47, 0
	v_readfirstlane_b32 s5, v162
	v_lshl_add_u64 v[160:161], s[18:19], 0, v[0:1]
	s_mov_b32 m0, s5
	v_readfirstlane_b32 s5, v163
	ds_read_b128 v[132:135], v147
	ds_read_b128 v[136:139], v147 offset:1024
	ds_read_b128 v[148:151], v147 offset:2048
	ds_read_b128 v[152:155], v147 offset:3072
	ds_read_b128 v[156:159], v146
	ds_read_b128 v[164:167], v146 offset:1024
	ds_read_b128 v[168:171], v146 offset:2048
	ds_read_b128 v[172:175], v146 offset:3072
	ds_read_b128 v[176:179], v146 offset:4096
	ds_read_b128 v[180:183], v146 offset:5120
	ds_read_b128 v[188:191], v146 offset:6144
	ds_read_b128 v[192:195], v146 offset:7168
	global_load_lds_dwordx4 v[160:161], off
	v_lshl_add_u64 v[130:131], s[18:19], 0, v[130:131]
	s_mov_b32 m0, s5
	s_nop 0
	global_load_lds_dwordx4 v[130:131], off
	s_waitcnt vmcnt(10)
	s_barrier
	s_waitcnt lgkmcnt(0)
	s_setprio 1
	s_waitcnt lgkmcnt(0)
	v_mfma_f32_16x16x32_bf16 v[126:129], v[156:159], v[132:135], v[126:129]
	v_mfma_f32_16x16x32_bf16 v[122:125], v[156:159], v[148:151], v[122:125]
	v_mfma_f32_16x16x32_bf16 v[118:121], v[168:171], v[132:135], v[118:121]
	v_mfma_f32_16x16x32_bf16 v[110:113], v[176:179], v[132:135], v[110:113]
	v_mfma_f32_16x16x32_bf16 v[106:109], v[176:179], v[148:151], v[106:109]
	v_mfma_f32_16x16x32_bf16 v[102:105], v[188:191], v[132:135], v[102:105]
	v_mfma_f32_16x16x32_bf16 v[98:101], v[188:191], v[148:151], v[98:101]
	v_mfma_f32_16x16x32_bf16 v[126:129], v[164:167], v[136:139], v[126:129]
	v_mfma_f32_16x16x32_bf16 v[122:125], v[164:167], v[152:155], v[122:125]
	v_mfma_f32_16x16x32_bf16 v[118:121], v[172:175], v[136:139], v[118:121]
	v_mfma_f32_16x16x32_bf16 v[114:117], v[168:171], v[148:151], v[114:117]
	v_mfma_f32_16x16x32_bf16 v[110:113], v[180:183], v[136:139], v[110:113]
	v_mfma_f32_16x16x32_bf16 v[106:109], v[180:183], v[152:155], v[106:109]
	v_mfma_f32_16x16x32_bf16 v[102:105], v[192:195], v[136:139], v[102:105]
	v_mfma_f32_16x16x32_bf16 v[98:101], v[192:195], v[152:155], v[98:101]
	v_mfma_f32_16x16x32_bf16 v[160:163], v[172:175], v[152:155], v[114:117]
	s_setprio 0
	s_barrier
; #define STAGE_A(Pp, br, kt) { const char* g_ = (const char*)(A + (size_t)(br) * lda + (size_t)(kt) * BK); \
;     __builtin_amdgcn_global_load_lds((const unsigned*)(g_ + oa0), (LAS unsigned*)((Pp) + tid * 16), 16, 0, 0); \
;     __builtin_amdgcn_global_load_lds((const unsigned*)(g_ + oa1), (LAS unsigned*)((Pp) + tid * 16 + 8192), 16, 0, 0); }
; #define LDA8(dst, b, h) _Pragma("unroll") for (int m = 0; m < 4; ++m) _Pragma("unroll") for (int k = 0; k < 2; ++k) \
;     dst[m][k] = *(const bf16x8*)(lrda + ((b) * 2 + (h)) * HTB + (2 * m + k) * 1024)
; #define LDB8(dst, b, h) _Pragma("unroll") for (int n = 0; n < 2; ++n) _Pragma("unroll") for (int k = 0; k < 2; ++k) \
;     dst[n][k] = *(const bf16x8*)(lrdb + ((b) * 2 + (h)) * HTB + (2 * n + k) * 1024)
; #define MMA8(ai, bj, AT, BT) { __builtin_amdgcn_s_setprio(1); \
;     _Pragma("unroll") for (int m = 0; m < 4; ++m) _Pragma("unroll") for (int n = 0; n < 2; ++n) _Pragma("unroll") for (int k = 0; k < 2; ++k) \
;       acc[ai][bj][m][n] = __builtin_amdgcn_mfma_f32_16x16x32_bf16(AT[m][k], BT[n][k], acc[ai][bj][m][n], 0, 0, 0); \
;     __builtin_amdgcn_s_setprio(0); }
; #define WAIT_V(n) asm volatile("s_waitcnt vmcnt(" #n ")" ::: "memory")
; #define WAIT_L(n) asm volatile("s_waitcnt lgkmcnt(" #n ")" ::: "memory")
; #define BAR8 __builtin_amdgcn_s_barrier()
; template <class Epi>
; DI void gemm256(const bf16_t* __restrict__ A, int lda, const bf16_t* __restrict__ Bt, int ldb, int K, char* lds, Epi epi) {
;     ...
;   { LDB8(B0, 0, 0); LDA8(At, 0, 0); STAGE_A(SA8(1, 1), HALFR, nt - 1);
;     BAR8; WAIT_L(0); MMA8(0, 0, At, B0); BAR8;
;     LDB8(B1, 0, 1); BAR8; WAIT_L(0); MMA8(0, 1, At, B1); BAR8;
;     LDA8(At, 0, 1); WAIT_V(4); BAR8; WAIT_L(0); MMA8(1, 0, At, B0); MMA8(1, 1, At, B1); BAR8; }
;   { LDB8(B0, 1, 0); LDA8(At, 1, 0); WAIT_V(2); BAR8; WAIT_L(0); MMA8(0, 0, At, B0); BAR8;
;     LDB8(B1, 1, 1); WAIT_V(0); BAR8; WAIT_L(0); MMA8(0, 1, At, B1); BAR8;
;     LDA8(At, 1, 1); BAR8; WAIT_L(0); MMA8(1, 0, At, B0); MMA8(1, 1, At, B1); BAR8; }
	s_nop 0
	ds_read_b128 v[114:117], v147 offset:16384
	ds_read_b128 v[216:219], v147 offset:17408
	ds_read_b128 v[220:223], v147 offset:18432
	ds_read_b128 v[224:227], v147 offset:19456
	s_waitcnt vmcnt(8)
	s_barrier
	s_waitcnt lgkmcnt(0)
	s_setprio 1
	s_waitcnt lgkmcnt(0)
	v_mfma_f32_16x16x32_bf16 v[90:93], v[156:159], v[220:223], v[90:93]
	v_mfma_f32_16x16x32_bf16 v[86:89], v[168:171], v[114:117], v[86:89]
	v_mfma_f32_16x16x32_bf16 v[94:97], v[156:159], v[114:117], v[94:97]
	v_mfma_f32_16x16x32_bf16 v[90:93], v[164:167], v[224:227], v[90:93]
	v_mfma_f32_16x16x32_bf16 v[86:89], v[172:175], v[216:219], v[86:89]
	v_mfma_f32_16x16x32_bf16 v[82:85], v[168:171], v[220:223], v[82:85]
	v_mfma_f32_16x16x32_bf16 v[78:81], v[176:179], v[114:117], v[78:81]
	v_mfma_f32_16x16x32_bf16 v[74:77], v[176:179], v[220:223], v[74:77]
	v_mfma_f32_16x16x32_bf16 v[70:73], v[188:191], v[114:117], v[70:73]
	v_mfma_f32_16x16x32_bf16 v[66:69], v[188:191], v[220:223], v[66:69]
	v_mfma_f32_16x16x32_bf16 v[228:231], v[164:167], v[216:219], v[94:97]
	v_mfma_f32_16x16x32_bf16 v[156:159], v[172:175], v[224:227], v[82:85]
	v_mfma_f32_16x16x32_bf16 v[164:167], v[180:183], v[216:219], v[78:81]
	v_mfma_f32_16x16x32_bf16 v[168:171], v[180:183], v[224:227], v[74:77]
	v_mfma_f32_16x16x32_bf16 v[172:175], v[192:195], v[216:219], v[70:73]
	v_mfma_f32_16x16x32_bf16 v[176:179], v[192:195], v[224:227], v[66:69]
	s_setprio 0
	s_barrier
	s_nop 0
	ds_read_b128 v[66:69], v146 offset:16384
	ds_read_b128 v[70:73], v146 offset:17408
	ds_read_b128 v[74:77], v146 offset:18432
	ds_read_b128 v[78:81], v146 offset:19456
	ds_read_b128 v[82:85], v146 offset:20480
	ds_read_b128 v[94:97], v146 offset:21504
	ds_read_b128 v[180:183], v146 offset:22528
	ds_read_b128 v[188:191], v146 offset:23552
	s_waitcnt vmcnt(4)
	s_barrier
	s_waitcnt lgkmcnt(0)
	s_setprio 1
	s_waitcnt lgkmcnt(0)
	v_mfma_f32_16x16x32_bf16 v[62:65], v[66:69], v[132:135], v[62:65]
	v_mfma_f32_16x16x32_bf16 v[58:61], v[66:69], v[148:151], v[58:61]
	v_mfma_f32_16x16x32_bf16 v[54:57], v[74:77], v[132:135], v[54:57]
	v_mfma_f32_16x16x32_bf16 v[50:53], v[74:77], v[148:151], v[50:53]
	v_mfma_f32_16x16x32_bf16 v[46:49], v[82:85], v[132:135], v[46:49]
	v_mfma_f32_16x16x32_bf16 v[42:45], v[82:85], v[148:151], v[42:45]
	v_mfma_f32_16x16x32_bf16 v[38:41], v[180:183], v[132:135], v[38:41]
	v_mfma_f32_16x16x32_bf16 v[34:37], v[180:183], v[148:151], v[34:37]
	v_mfma_f32_16x16x32_bf16 v[62:65], v[70:73], v[136:139], v[62:65]
	v_mfma_f32_16x16x32_bf16 v[58:61], v[70:73], v[152:155], v[58:61]
	v_mfma_f32_16x16x32_bf16 v[54:57], v[78:81], v[136:139], v[54:57]
	v_mfma_f32_16x16x32_bf16 v[50:53], v[78:81], v[152:155], v[50:53]
	v_mfma_f32_16x16x32_bf16 v[46:49], v[94:97], v[136:139], v[46:49]
	v_mfma_f32_16x16x32_bf16 v[42:45], v[94:97], v[152:155], v[42:45]
	v_mfma_f32_16x16x32_bf16 v[38:41], v[188:191], v[136:139], v[38:41]
	v_mfma_f32_16x16x32_bf16 v[34:37], v[188:191], v[152:155], v[34:37]
	s_setprio 0
	s_setprio 1
	v_mfma_f32_16x16x32_bf16 v[30:33], v[66:69], v[114:117], v[30:33]
	v_mfma_f32_16x16x32_bf16 v[26:29], v[66:69], v[220:223], v[26:29]
	v_mfma_f32_16x16x32_bf16 v[22:25], v[74:77], v[114:117], v[22:25]
	v_mfma_f32_16x16x32_bf16 v[18:21], v[74:77], v[220:223], v[18:21]
	v_mfma_f32_16x16x32_bf16 v[14:17], v[82:85], v[114:117], v[14:17]
	v_mfma_f32_16x16x32_bf16 v[10:13], v[82:85], v[220:223], v[10:13]
	v_mfma_f32_16x16x32_bf16 v[6:9], v[180:183], v[114:117], v[6:9]
	v_mfma_f32_16x16x32_bf16 v[2:5], v[180:183], v[220:223], v[2:5]
	v_mfma_f32_16x16x32_bf16 v[130:133], v[70:73], v[216:219], v[30:33]
	v_mfma_f32_16x16x32_bf16 v[134:137], v[70:73], v[224:227], v[26:29]
	v_mfma_f32_16x16x32_bf16 v[148:151], v[78:81], v[216:219], v[22:25]
	v_mfma_f32_16x16x32_bf16 v[152:155], v[78:81], v[224:227], v[18:21]
	v_mfma_f32_16x16x32_bf16 v[192:195], v[94:97], v[216:219], v[14:17]
	v_mfma_f32_16x16x32_bf16 v[232:235], v[94:97], v[224:227], v[10:13]
	v_mfma_f32_16x16x32_bf16 v[216:219], v[188:191], v[216:219], v[6:9]
	v_mfma_f32_16x16x32_bf16 v[180:183], v[188:191], v[224:227], v[2:5]
	s_setprio 0
	s_barrier
	ds_read_b128 v[14:17], v147 offset:32768
	ds_read_b128 v[30:33], v147 offset:33792
	ds_read_b128 v[188:191], v147 offset:34816
	ds_read_b128 v[220:223], v147 offset:35840
	ds_read_b128 v[2:5], v146 offset:32768
	ds_read_b128 v[6:9], v146 offset:33792
	ds_read_b128 v[10:13], v146 offset:34816
	ds_read_b128 v[18:21], v146 offset:35840
	ds_read_b128 v[22:25], v146 offset:36864
	ds_read_b128 v[26:29], v146 offset:37888
	ds_read_b128 v[224:227], v146 offset:38912
	ds_read_b128 v[236:239], v146 offset:39936
	s_waitcnt vmcnt(2)
	s_barrier
; #define LDA8(dst, b, h) _Pragma("unroll") for (int m = 0; m < 4; ++m) _Pragma("unroll") for (int k = 0; k < 2; ++k) \
;     dst[m][k] = *(const bf16x8*)(lrda + ((b) * 2 + (h)) * HTB + (2 * m + k) * 1024)
; #define LDB8(dst, b, h) _Pragma("unroll") for (int n = 0; n < 2; ++n) _Pragma("unroll") for (int k = 0; k < 2; ++k) \
;     dst[n][k] = *(const bf16x8*)(lrdb + ((b) * 2 + (h)) * HTB + (2 * n + k) * 1024)
; #define MMA8(ai, bj, AT, BT) { __builtin_amdgcn_s_setprio(1); \
;     _Pragma("unroll") for (int m = 0; m < 4; ++m) _Pragma("unroll") for (int n = 0; n < 2; ++n) _Pragma("unroll") for (int k = 0; k < 2; ++k) \
;       acc[ai][bj][m][n] = __builtin_amdgcn_mfma_f32_16x16x32_bf16(AT[m][k], BT[n][k], acc[ai][bj][m][n], 0, 0, 0); \
;     __builtin_amdgcn_s_setprio(0); }
; #define WAIT_V(n) asm volatile("s_waitcnt vmcnt(" #n ")" ::: "memory")
; #define WAIT_L(n) asm volatile("s_waitcnt lgkmcnt(" #n ")" ::: "memory")
; #define BAR8 __builtin_amdgcn_s_barrier()
; template <class Epi>
; DI void gemm256(const bf16_t* __restrict__ A, int lda, const bf16_t* __restrict__ Bt, int ldb, int K, char* lds, Epi epi) {
;     ...
;   { LDB8(B0, 1, 0); LDA8(At, 1, 0); WAIT_V(2); BAR8; WAIT_L(0); MMA8(0, 0, At, B0); BAR8;
;     LDB8(B1, 1, 1); WAIT_V(0); BAR8; WAIT_L(0); MMA8(0, 1, At, B1); BAR8;
;     LDA8(At, 1, 1); BAR8; WAIT_L(0); MMA8(1, 0, At, B0); MMA8(1, 1, At, B1); BAR8; }
;   if (wr == 0) BAR8;
	s_waitcnt lgkmcnt(0)
	s_setprio 1
	s_waitcnt lgkmcnt(0)
	v_mfma_f32_16x16x32_bf16 v[66:69], v[2:5], v[14:17], v[126:129]
	v_mfma_f32_16x16x32_bf16 v[114:117], v[6:9], v[30:33], v[66:69]
	v_mfma_f32_16x16x32_bf16 v[66:69], v[2:5], v[188:191], v[122:125]
	v_mfma_f32_16x16x32_bf16 v[126:129], v[6:9], v[220:223], v[66:69]
	v_mfma_f32_16x16x32_bf16 v[66:69], v[10:13], v[14:17], v[118:121]
	v_mfma_f32_16x16x32_bf16 v[82:85], v[18:21], v[30:33], v[66:69]
	v_mfma_f32_16x16x32_bf16 v[66:69], v[10:13], v[188:191], v[160:163]
	v_mfma_f32_16x16x32_bf16 v[94:97], v[18:21], v[220:223], v[66:69]
	v_mfma_f32_16x16x32_bf16 v[66:69], v[22:25], v[14:17], v[110:113]
	v_mfma_f32_16x16x32_bf16 v[74:77], v[26:29], v[30:33], v[66:69]
	v_mfma_f32_16x16x32_bf16 v[66:69], v[22:25], v[188:191], v[106:109]
	v_mfma_f32_16x16x32_bf16 v[78:81], v[26:29], v[220:223], v[66:69]
	v_mfma_f32_16x16x32_bf16 v[66:69], v[224:227], v[14:17], v[102:105]
	v_mfma_f32_16x16x32_bf16 v[70:73], v[224:227], v[188:191], v[98:101]
	v_mfma_f32_16x16x32_bf16 v[66:69], v[236:239], v[30:33], v[66:69]
	v_mfma_f32_16x16x32_bf16 v[70:73], v[236:239], v[220:223], v[70:73]
	s_setprio 0
	s_barrier
	ds_read_b128 v[160:163], v147 offset:49152
	ds_read_b128 v[240:243], v147 offset:50176
	ds_read_b128 v[244:247], v147 offset:51200
	ds_read_b128 v[248:251], v147 offset:52224
	s_waitcnt vmcnt(0)
	s_barrier
	s_waitcnt lgkmcnt(0)
	s_setprio 1
	s_waitcnt lgkmcnt(0)
	v_mfma_f32_16x16x32_bf16 v[98:101], v[2:5], v[160:163], v[228:231]
	v_mfma_f32_16x16x32_bf16 v[2:5], v[2:5], v[244:247], v[90:93]
	v_mfma_f32_16x16x32_bf16 v[118:121], v[6:9], v[248:251], v[2:5]
	v_mfma_f32_16x16x32_bf16 v[2:5], v[10:13], v[160:163], v[86:89]
	v_mfma_f32_16x16x32_bf16 v[102:105], v[18:21], v[240:243], v[2:5]
	v_mfma_f32_16x16x32_bf16 v[2:5], v[10:13], v[244:247], v[156:159]
	v_mfma_f32_16x16x32_bf16 v[122:125], v[18:21], v[248:251], v[2:5]
	v_mfma_f32_16x16x32_bf16 v[2:5], v[22:25], v[160:163], v[164:167]
	v_mfma_f32_16x16x32_bf16 v[90:93], v[26:29], v[240:243], v[2:5]
	v_mfma_f32_16x16x32_bf16 v[2:5], v[22:25], v[244:247], v[168:171]
	v_mfma_f32_16x16x32_bf16 v[110:113], v[26:29], v[248:251], v[2:5]
	v_mfma_f32_16x16x32_bf16 v[2:5], v[224:227], v[160:163], v[172:175]
	v_mfma_f32_16x16x32_bf16 v[86:89], v[236:239], v[240:243], v[2:5]
	v_mfma_f32_16x16x32_bf16 v[2:5], v[224:227], v[244:247], v[176:179]
	v_mfma_f32_16x16x32_bf16 v[98:101], v[6:9], v[240:243], v[98:101]
	v_mfma_f32_16x16x32_bf16 v[106:109], v[236:239], v[248:251], v[2:5]
	s_setprio 0
	s_barrier
	ds_read_b128 v[156:159], v146 offset:49152
	ds_read_b128 v[164:167], v146 offset:50176
	ds_read_b128 v[168:171], v146 offset:51200
	ds_read_b128 v[172:175], v146 offset:52224
	ds_read_b128 v[176:179], v146 offset:53248
	ds_read_b128 v[224:227], v146 offset:54272
	ds_read_b128 v[228:231], v146 offset:55296
	ds_read_b128 v[236:239], v146 offset:56320
	s_barrier
	s_waitcnt lgkmcnt(0)
	s_setprio 1
	s_waitcnt lgkmcnt(0)
	v_mfma_f32_16x16x32_bf16 v[6:9], v[156:159], v[188:191], v[58:61]
	v_mfma_f32_16x16x32_bf16 v[10:13], v[168:171], v[188:191], v[50:53]
	v_mfma_f32_16x16x32_bf16 v[2:5], v[156:159], v[14:17], v[62:65]
	v_mfma_f32_16x16x32_bf16 v[18:21], v[164:167], v[220:223], v[6:9]
	v_mfma_f32_16x16x32_bf16 v[6:9], v[168:171], v[14:17], v[54:57]
	v_mfma_f32_16x16x32_bf16 v[22:25], v[172:175], v[220:223], v[10:13]
	v_mfma_f32_16x16x32_bf16 v[10:13], v[176:179], v[14:17], v[46:49]
	v_mfma_f32_16x16x32_bf16 v[14:17], v[228:231], v[14:17], v[38:41]
	v_mfma_f32_16x16x32_bf16 v[2:5], v[164:167], v[30:33], v[2:5]
	v_mfma_f32_16x16x32_bf16 v[6:9], v[172:175], v[30:33], v[6:9]
	v_mfma_f32_16x16x32_bf16 v[10:13], v[224:227], v[30:33], v[10:13]
	v_mfma_f32_16x16x32_bf16 v[26:29], v[176:179], v[188:191], v[42:45]
	v_mfma_f32_16x16x32_bf16 v[14:17], v[236:239], v[30:33], v[14:17]
	v_mfma_f32_16x16x32_bf16 v[30:33], v[228:231], v[188:191], v[34:37]
	v_mfma_f32_16x16x32_bf16 v[26:29], v[224:227], v[220:223], v[26:29]
	v_mfma_f32_16x16x32_bf16 v[30:33], v[236:239], v[220:223], v[30:33]
	s_setprio 0
	s_setprio 1
	v_mfma_f32_16x16x32_bf16 v[38:41], v[156:159], v[244:247], v[134:137]
	v_mfma_f32_16x16x32_bf16 v[42:45], v[168:171], v[244:247], v[152:155]
	v_mfma_f32_16x16x32_bf16 v[46:49], v[176:179], v[244:247], v[232:235]
	v_mfma_f32_16x16x32_bf16 v[34:37], v[156:159], v[160:163], v[130:133]
	v_mfma_f32_16x16x32_bf16 v[50:53], v[164:167], v[248:251], v[38:41]
	v_mfma_f32_16x16x32_bf16 v[38:41], v[168:171], v[160:163], v[148:151]
	v_mfma_f32_16x16x32_bf16 v[54:57], v[172:175], v[248:251], v[42:45]
	v_mfma_f32_16x16x32_bf16 v[42:45], v[176:179], v[160:163], v[192:195]
	v_mfma_f32_16x16x32_bf16 v[58:61], v[224:227], v[248:251], v[46:49]
	v_mfma_f32_16x16x32_bf16 v[46:49], v[228:231], v[160:163], v[216:219]
	v_mfma_f32_16x16x32_bf16 v[62:65], v[228:231], v[244:247], v[180:183]
	v_mfma_f32_16x16x32_bf16 v[34:37], v[164:167], v[240:243], v[34:37]
	v_mfma_f32_16x16x32_bf16 v[38:41], v[172:175], v[240:243], v[38:41]
	v_mfma_f32_16x16x32_bf16 v[42:45], v[224:227], v[240:243], v[42:45]
	v_mfma_f32_16x16x32_bf16 v[46:49], v[236:239], v[240:243], v[46:49]
	v_mfma_f32_16x16x32_bf16 v[62:65], v[236:239], v[248:251], v[62:65]
	s_setprio 0
	s_movk_i32 s5, 0x100
	v_cmp_gt_u32_e32 vcc, s5, v140
	s_barrier
	s_and_saveexec_b64 s[18:19], vcc
	s_cbranch_execz .LBB0_321
	s_barrier

; #define STAGE_A(Pp, br, kt) { const char* g_ = (const char*)(A + (size_t)(br) * lda + (size_t)(kt) * BK); \
;     __builtin_amdgcn_global_load_lds((const unsigned*)(g_ + oa0), (LAS unsigned*)((Pp) + tid * 16), 16, 0, 0); \
;     __builtin_amdgcn_global_load_lds((const unsigned*)(g_ + oa1), (LAS unsigned*)((Pp) + tid * 16 + 8192), 16, 0, 0); }
; #define STAGE_B(Pp, br, kt) { const char* g_ = (const char*)(Bt + (size_t)(br) * ldb + (size_t)(kt) * BK); \
;     __builtin_amdgcn_global_load_lds((const unsigned*)(g_ + ob0), (LAS unsigned*)((Pp) + tid * 16), 16, 0, 0); \
;     __builtin_amdgcn_global_load_lds((const unsigned*)(g_ + ob1), (LAS unsigned*)((Pp) + tid * 16 + 8192), 16, 0, 0); }
; #define LDA8(dst, b, h) _Pragma("unroll") for (int m = 0; m < 4; ++m) _Pragma("unroll") for (int k = 0; k < 2; ++k) \
;     dst[m][k] = *(const bf16x8*)(lrda + ((b) * 2 + (h)) * HTB + (2 * m + k) * 1024)
; #define LDB8(dst, b, h) _Pragma("unroll") for (int n = 0; n < 2; ++n) _Pragma("unroll") for (int k = 0; k < 2; ++k) \
;     dst[n][k] = *(const bf16x8*)(lrdb + ((b) * 2 + (h)) * HTB + (2 * n + k) * 1024)
; #define MMA8(ai, bj, AT, BT) { __builtin_amdgcn_s_setprio(1); \
;     _Pragma("unroll") for (int m = 0; m < 4; ++m) _Pragma("unroll") for (int n = 0; n < 2; ++n) _Pragma("unroll") for (int k = 0; k < 2; ++k) \
;       acc[ai][bj][m][n] = __builtin_amdgcn_mfma_f32_16x16x32_bf16(AT[m][k], BT[n][k], acc[ai][bj][m][n], 0, 0, 0); \
;     __builtin_amdgcn_s_setprio(0); }
; #define WAIT_L(n) asm volatile("s_waitcnt lgkmcnt(" #n ")" ::: "memory")
; #define BAR8 __builtin_amdgcn_s_barrier()
; #define SCHED8 __builtin_amdgcn_sched_barrier(0)
; template <class Epi>
; DI void gemm256(const bf16_t* __restrict__ A, int lda, const bf16_t* __restrict__ Bt, int ldb, int K, char* lds, Epi epi) {
;     ...
;     LDB8(B0, 0, 0); SCHED8; LDA8(At, 0, 0); STAGE_A(SA8(1, 1), HALFR, t + 1);
;     WAIT_L(8); BAR8; WAIT_L(0); MMA8(0, 0, At, B0); BAR8; SCHED8;
;     LDB8(B1, 0, 1); STAGE_B(SB8(0, 0), 0, t + 2);
;     BAR8; WAIT_L(0); MMA8(0, 1, At, B1); BAR8;
;     LDA8(At, 0, 1); STAGE_A(SA8(0, 0), 0, t + 2);
;     BAR8; WAIT_L(0); MMA8(1, 0, At, B0); BAR8; SCHED8;
.LBB0_346:
	ds_read_b128 v[164:167], v147
	ds_read_b128 v[168:171], v147 offset:1024
	ds_read_b128 v[172:175], v147 offset:2048
	ds_read_b128 v[176:179], v147 offset:3072
	v_add_u32_e32 v162, 0xc000, v150
	v_lshl_add_u64 v[184:185], s[36:37], 0, v[134:135]
	v_readfirstlane_b32 s5, v162
	v_lshl_add_u64 v[202:203], v[184:185], 0, s[38:39]
	s_mov_b32 m0, s5
	v_add_u32_e32 v163, 0xe000, v150
	ds_read_b128 v[180:183], v146
	ds_read_b128 v[188:191], v146 offset:1024
	ds_read_b128 v[192:195], v146 offset:2048
	ds_read_b128 v[216:219], v146 offset:3072
	ds_read_b128 v[220:223], v146 offset:4096
	ds_read_b128 v[224:227], v146 offset:5120
	ds_read_b128 v[228:231], v146 offset:6144
	ds_read_b128 v[232:235], v146 offset:7168
	global_load_lds_dwordx4 v[202:203], off
	v_lshl_add_u64 v[202:203], s[36:37], 0, v[132:133]
	v_readfirstlane_b32 s5, v163
	v_lshl_add_u64 v[210:211], v[202:203], 0, s[38:39]
	s_mov_b32 m0, s5
	s_nop 0
	global_load_lds_dwordx4 v[210:211], off
	s_waitcnt lgkmcnt(8)
	s_waitcnt vmcnt(10)
	s_barrier
	s_waitcnt lgkmcnt(0)
	s_setprio 1
	s_waitcnt lgkmcnt(0)
	v_mfma_f32_16x16x32_bf16 v[126:129], v[180:183], v[164:167], v[126:129]
	v_mfma_f32_16x16x32_bf16 v[122:125], v[180:183], v[172:175], v[122:125]
	v_mfma_f32_16x16x32_bf16 v[118:121], v[192:195], v[164:167], v[118:121]
	v_mfma_f32_16x16x32_bf16 v[114:117], v[192:195], v[172:175], v[114:117]
	v_mfma_f32_16x16x32_bf16 v[110:113], v[220:223], v[164:167], v[110:113]
	v_mfma_f32_16x16x32_bf16 v[106:109], v[220:223], v[172:175], v[106:109]
	v_mfma_f32_16x16x32_bf16 v[102:105], v[228:231], v[164:167], v[102:105]
	v_mfma_f32_16x16x32_bf16 v[98:101], v[228:231], v[172:175], v[98:101]
	v_mfma_f32_16x16x32_bf16 v[126:129], v[188:191], v[168:171], v[126:129]
	v_mfma_f32_16x16x32_bf16 v[122:125], v[188:191], v[176:179], v[122:125]
	v_mfma_f32_16x16x32_bf16 v[118:121], v[216:219], v[168:171], v[118:121]
	v_mfma_f32_16x16x32_bf16 v[114:117], v[216:219], v[176:179], v[114:117]
	v_mfma_f32_16x16x32_bf16 v[110:113], v[224:227], v[168:171], v[110:113]
	v_mfma_f32_16x16x32_bf16 v[106:109], v[224:227], v[176:179], v[106:109]
	v_mfma_f32_16x16x32_bf16 v[102:105], v[232:235], v[168:171], v[102:105]
	v_mfma_f32_16x16x32_bf16 v[98:101], v[232:235], v[176:179], v[98:101]
	s_setprio 0
	s_barrier
	v_lshl_add_u64 v[210:211], s[36:37], 0, v[138:139]
	v_readfirstlane_b32 s5, v148
	v_lshl_add_u64 v[212:213], v[210:211], 0, s[92:93]
	s_mov_b32 m0, s5
	ds_read_b128 v[236:239], v147 offset:16384
	ds_read_b128 v[240:243], v147 offset:17408
	ds_read_b128 v[244:247], v147 offset:18432
	ds_read_b128 v[248:251], v147 offset:19456
	global_load_lds_dwordx4 v[212:213], off
	v_lshl_add_u64 v[212:213], s[36:37], 0, v[136:137]
	v_readfirstlane_b32 s5, v149
	v_lshl_add_u64 v[214:215], v[212:213], 0, s[92:93]
	s_mov_b32 m0, s5
	s_nop 0
	global_load_lds_dwordx4 v[214:215], off
	s_waitcnt vmcnt(10)
	s_barrier
	s_waitcnt lgkmcnt(0)
	s_setprio 1
	s_waitcnt lgkmcnt(0)
	v_mfma_f32_16x16x32_bf16 v[94:97], v[180:183], v[236:239], v[94:97]
	v_mfma_f32_16x16x32_bf16 v[90:93], v[180:183], v[244:247], v[90:93]
	v_mfma_f32_16x16x32_bf16 v[86:89], v[192:195], v[236:239], v[86:89]
	v_mfma_f32_16x16x32_bf16 v[82:85], v[192:195], v[244:247], v[82:85]
	v_mfma_f32_16x16x32_bf16 v[78:81], v[220:223], v[236:239], v[78:81]
	v_mfma_f32_16x16x32_bf16 v[74:77], v[220:223], v[244:247], v[74:77]
	v_mfma_f32_16x16x32_bf16 v[70:73], v[228:231], v[236:239], v[70:73]
	v_mfma_f32_16x16x32_bf16 v[66:69], v[228:231], v[244:247], v[66:69]
	v_mfma_f32_16x16x32_bf16 v[94:97], v[188:191], v[240:243], v[94:97]
	v_mfma_f32_16x16x32_bf16 v[90:93], v[188:191], v[248:251], v[90:93]
	v_mfma_f32_16x16x32_bf16 v[86:89], v[216:219], v[240:243], v[86:89]
	v_mfma_f32_16x16x32_bf16 v[82:85], v[216:219], v[248:251], v[82:85]
	v_mfma_f32_16x16x32_bf16 v[78:81], v[224:227], v[240:243], v[78:81]
	v_mfma_f32_16x16x32_bf16 v[74:77], v[224:227], v[248:251], v[74:77]
	v_mfma_f32_16x16x32_bf16 v[70:73], v[232:235], v[240:243], v[70:73]
	v_mfma_f32_16x16x32_bf16 v[66:69], v[232:235], v[248:251], v[66:69]
	s_setprio 0
	v_readfirstlane_b32 s5, v150
	v_lshl_add_u64 v[214:215], v[184:185], 0, s[66:67]
	s_mov_b32 m0, s5
	v_readfirstlane_b32 s5, v151
	s_barrier
	ds_read_b128 v[180:183], v146 offset:16384
	ds_read_b128 v[188:191], v146 offset:17408
	ds_read_b128 v[192:195], v146 offset:18432
	ds_read_b128 v[216:219], v146 offset:19456
	ds_read_b128 v[220:223], v146 offset:20480
	ds_read_b128 v[224:227], v146 offset:21504
	ds_read_b128 v[228:231], v146 offset:22528
	ds_read_b128 v[232:235], v146 offset:23552
	global_load_lds_dwordx4 v[214:215], off
	v_lshl_add_u64 v[214:215], v[202:203], 0, s[66:67]
	s_mov_b32 m0, s5
	s_nop 0
	global_load_lds_dwordx4 v[214:215], off
	s_barrier
	s_waitcnt lgkmcnt(0)
	s_setprio 1
	s_waitcnt lgkmcnt(0)
	v_mfma_f32_16x16x32_bf16 v[62:65], v[180:183], v[164:167], v[62:65]
	v_mfma_f32_16x16x32_bf16 v[58:61], v[180:183], v[172:175], v[58:61]
	v_mfma_f32_16x16x32_bf16 v[54:57], v[192:195], v[164:167], v[54:57]
	v_mfma_f32_16x16x32_bf16 v[50:53], v[192:195], v[172:175], v[50:53]
	v_mfma_f32_16x16x32_bf16 v[46:49], v[220:223], v[164:167], v[46:49]
	v_mfma_f32_16x16x32_bf16 v[42:45], v[220:223], v[172:175], v[42:45]
	v_mfma_f32_16x16x32_bf16 v[38:41], v[228:231], v[164:167], v[38:41]
	v_mfma_f32_16x16x32_bf16 v[34:37], v[228:231], v[172:175], v[34:37]
	v_mfma_f32_16x16x32_bf16 v[62:65], v[188:191], v[168:171], v[62:65]
	v_mfma_f32_16x16x32_bf16 v[58:61], v[188:191], v[176:179], v[58:61]
	v_mfma_f32_16x16x32_bf16 v[54:57], v[216:219], v[168:171], v[54:57]
	v_mfma_f32_16x16x32_bf16 v[50:53], v[216:219], v[176:179], v[50:53]
	v_mfma_f32_16x16x32_bf16 v[46:49], v[224:227], v[168:171], v[46:49]
	v_mfma_f32_16x16x32_bf16 v[42:45], v[224:227], v[176:179], v[42:45]
	v_mfma_f32_16x16x32_bf16 v[38:41], v[232:235], v[168:171], v[38:41]
	v_mfma_f32_16x16x32_bf16 v[34:37], v[232:235], v[176:179], v[34:37]
	s_setprio 0
	s_barrier
; #define STAGE_A(Pp, br, kt) { const char* g_ = (const char*)(A + (size_t)(br) * lda + (size_t)(kt) * BK); \
;     __builtin_amdgcn_global_load_lds((const unsigned*)(g_ + oa0), (LAS unsigned*)((Pp) + tid * 16), 16, 0, 0); \
;     __builtin_amdgcn_global_load_lds((const unsigned*)(g_ + oa1), (LAS unsigned*)((Pp) + tid * 16 + 8192), 16, 0, 0); }
; #define STAGE_B(Pp, br, kt) { const char* g_ = (const char*)(Bt + (size_t)(br) * ldb + (size_t)(kt) * BK); \
;     __builtin_amdgcn_global_load_lds((const unsigned*)(g_ + ob0), (LAS unsigned*)((Pp) + tid * 16), 16, 0, 0); \
;     __builtin_amdgcn_global_load_lds((const unsigned*)(g_ + ob1), (LAS unsigned*)((Pp) + tid * 16 + 8192), 16, 0, 0); }
; #define LDA8(dst, b, h) _Pragma("unroll") for (int m = 0; m < 4; ++m) _Pragma("unroll") for (int k = 0; k < 2; ++k) \
;     dst[m][k] = *(const bf16x8*)(lrda + ((b) * 2 + (h)) * HTB + (2 * m + k) * 1024)
; #define LDB8(dst, b, h) _Pragma("unroll") for (int n = 0; n < 2; ++n) _Pragma("unroll") for (int k = 0; k < 2; ++k) \
;     dst[n][k] = *(const bf16x8*)(lrdb + ((b) * 2 + (h)) * HTB + (2 * n + k) * 1024)
; #define MMA8(ai, bj, AT, BT) { __builtin_amdgcn_s_setprio(1); \
;     _Pragma("unroll") for (int m = 0; m < 4; ++m) _Pragma("unroll") for (int n = 0; n < 2; ++n) _Pragma("unroll") for (int k = 0; k < 2; ++k) \
;       acc[ai][bj][m][n] = __builtin_amdgcn_mfma_f32_16x16x32_bf16(AT[m][k], BT[n][k], acc[ai][bj][m][n], 0, 0, 0); \
;     __builtin_amdgcn_s_setprio(0); }
; #define WAIT_V(n) asm volatile("s_waitcnt vmcnt(" #n ")" ::: "memory")
; #define WAIT_L(n) asm volatile("s_waitcnt lgkmcnt(" #n ")" ::: "memory")
; #define BAR8 __builtin_amdgcn_s_barrier()
; #define SCHED8 __builtin_amdgcn_sched_barrier(0)
; template <class Epi>
; DI void gemm256(const bf16_t* __restrict__ A, int lda, const bf16_t* __restrict__ Bt, int ldb, int K, char* lds, Epi epi) {
;     ...
;     STAGE_B(SB8(0, 1), HALFR, t + 2);
;     WAIT_V(6); BAR8; MMA8(1, 1, At, B1); BAR8;
;     LDB8(B0, 1, 0); SCHED8; LDA8(At, 1, 0); STAGE_A(SA8(0, 1), HALFR, t + 2);
;     WAIT_L(8); BAR8; WAIT_L(0); MMA8(0, 0, At, B0); BAR8; SCHED8;
;     LDB8(B1, 1, 1); STAGE_B(SB8(1, 0), 0, t + 3);
;     BAR8; WAIT_L(0); MMA8(0, 1, At, B1); BAR8;
	v_readfirstlane_b32 s5, v152
	v_lshl_add_u64 v[164:165], v[210:211], 0, s[94:95]
	s_mov_b32 m0, s5
	v_readfirstlane_b32 s5, v153
	global_load_lds_dwordx4 v[164:165], off
	v_lshl_add_u64 v[164:165], v[212:213], 0, s[94:95]
	s_mov_b32 m0, s5
	s_nop 0
	global_load_lds_dwordx4 v[164:165], off
	s_waitcnt vmcnt(10)
	s_barrier
	s_setprio 1
	v_mfma_f32_16x16x32_bf16 v[30:33], v[180:183], v[236:239], v[30:33]
	v_mfma_f32_16x16x32_bf16 v[26:29], v[180:183], v[244:247], v[26:29]
	v_mfma_f32_16x16x32_bf16 v[22:25], v[192:195], v[236:239], v[22:25]
	v_mfma_f32_16x16x32_bf16 v[18:21], v[192:195], v[244:247], v[18:21]
	v_mfma_f32_16x16x32_bf16 v[14:17], v[220:223], v[236:239], v[14:17]
	v_mfma_f32_16x16x32_bf16 v[10:13], v[220:223], v[244:247], v[10:13]
	v_mfma_f32_16x16x32_bf16 v[6:9], v[228:231], v[236:239], v[6:9]
	v_mfma_f32_16x16x32_bf16 v[2:5], v[228:231], v[244:247], v[2:5]
	v_mfma_f32_16x16x32_bf16 v[30:33], v[188:191], v[240:243], v[30:33]
	v_mfma_f32_16x16x32_bf16 v[26:29], v[188:191], v[248:251], v[26:29]
	v_mfma_f32_16x16x32_bf16 v[22:25], v[216:219], v[240:243], v[22:25]
	v_mfma_f32_16x16x32_bf16 v[18:21], v[216:219], v[248:251], v[18:21]
	v_mfma_f32_16x16x32_bf16 v[14:17], v[224:227], v[240:243], v[14:17]
	v_mfma_f32_16x16x32_bf16 v[10:13], v[224:227], v[248:251], v[10:13]
	v_mfma_f32_16x16x32_bf16 v[6:9], v[232:235], v[240:243], v[6:9]
	v_mfma_f32_16x16x32_bf16 v[2:5], v[232:235], v[248:251], v[2:5]
	s_setprio 0
	s_barrier
	ds_read_b128 v[164:167], v147 offset:32768
	ds_read_b128 v[168:171], v147 offset:33792
	ds_read_b128 v[172:175], v147 offset:34816
	ds_read_b128 v[176:179], v147 offset:35840
	v_readfirstlane_b32 s5, v154
	v_lshl_add_u64 v[214:215], v[184:185], 0, s[16:17]
	s_mov_b32 m0, s5
	v_readfirstlane_b32 s5, v155
	ds_read_b128 v[180:183], v146 offset:32768
	ds_read_b128 v[188:191], v146 offset:33792
	ds_read_b128 v[192:195], v146 offset:34816
	ds_read_b128 v[216:219], v146 offset:35840
	ds_read_b128 v[220:223], v146 offset:36864
	ds_read_b128 v[224:227], v146 offset:37888
	ds_read_b128 v[228:231], v146 offset:38912
	ds_read_b128 v[232:235], v146 offset:39936
	global_load_lds_dwordx4 v[214:215], off
	v_lshl_add_u64 v[214:215], v[202:203], 0, s[16:17]
	s_mov_b32 m0, s5
	s_nop 0
	global_load_lds_dwordx4 v[214:215], off
	s_waitcnt lgkmcnt(8)
	s_waitcnt vmcnt(10)
	s_barrier
	s_waitcnt lgkmcnt(0)
	s_setprio 1
	s_waitcnt lgkmcnt(0)
	v_mfma_f32_16x16x32_bf16 v[126:129], v[180:183], v[164:167], v[126:129]
	v_mfma_f32_16x16x32_bf16 v[122:125], v[180:183], v[172:175], v[122:125]
	v_mfma_f32_16x16x32_bf16 v[118:121], v[192:195], v[164:167], v[118:121]
	v_mfma_f32_16x16x32_bf16 v[114:117], v[192:195], v[172:175], v[114:117]
	v_mfma_f32_16x16x32_bf16 v[110:113], v[220:223], v[164:167], v[110:113]
	v_mfma_f32_16x16x32_bf16 v[106:109], v[220:223], v[172:175], v[106:109]
	v_mfma_f32_16x16x32_bf16 v[102:105], v[228:231], v[164:167], v[102:105]
	v_mfma_f32_16x16x32_bf16 v[98:101], v[228:231], v[172:175], v[98:101]
	v_mfma_f32_16x16x32_bf16 v[126:129], v[188:191], v[168:171], v[126:129]
	v_mfma_f32_16x16x32_bf16 v[122:125], v[188:191], v[176:179], v[122:125]
	v_mfma_f32_16x16x32_bf16 v[118:121], v[216:219], v[168:171], v[118:121]
	v_mfma_f32_16x16x32_bf16 v[114:117], v[216:219], v[176:179], v[114:117]
	v_mfma_f32_16x16x32_bf16 v[110:113], v[224:227], v[168:171], v[110:113]
	v_mfma_f32_16x16x32_bf16 v[106:109], v[224:227], v[176:179], v[106:109]
	v_mfma_f32_16x16x32_bf16 v[102:105], v[232:235], v[168:171], v[102:105]
	v_mfma_f32_16x16x32_bf16 v[98:101], v[232:235], v[176:179], v[98:101]
	s_setprio 0
	s_barrier
	v_readfirstlane_b32 s5, v156
	v_lshl_add_u64 v[214:215], v[210:211], 0, s[96:97]
	s_mov_b32 m0, s5
	v_readfirstlane_b32 s5, v157
	ds_read_b128 v[236:239], v147 offset:49152
	ds_read_b128 v[240:243], v147 offset:50176
	ds_read_b128 v[244:247], v147 offset:51200
	ds_read_b128 v[248:251], v147 offset:52224
	global_load_lds_dwordx4 v[214:215], off
	v_lshl_add_u64 v[214:215], v[212:213], 0, s[96:97]
	s_mov_b32 m0, s5
	s_nop 0
	global_load_lds_dwordx4 v[214:215], off
	s_waitcnt vmcnt(10)
	s_barrier
	s_waitcnt lgkmcnt(0)
	s_setprio 1
	s_waitcnt lgkmcnt(0)
	v_mfma_f32_16x16x32_bf16 v[94:97], v[180:183], v[236:239], v[94:97]
	v_mfma_f32_16x16x32_bf16 v[90:93], v[180:183], v[244:247], v[90:93]
	v_mfma_f32_16x16x32_bf16 v[86:89], v[192:195], v[236:239], v[86:89]
	v_mfma_f32_16x16x32_bf16 v[82:85], v[192:195], v[244:247], v[82:85]
	v_mfma_f32_16x16x32_bf16 v[78:81], v[220:223], v[236:239], v[78:81]
	v_mfma_f32_16x16x32_bf16 v[74:77], v[220:223], v[244:247], v[74:77]
	v_mfma_f32_16x16x32_bf16 v[70:73], v[228:231], v[236:239], v[70:73]
	v_mfma_f32_16x16x32_bf16 v[66:69], v[228:231], v[244:247], v[66:69]
	v_mfma_f32_16x16x32_bf16 v[94:97], v[188:191], v[240:243], v[94:97]
	v_mfma_f32_16x16x32_bf16 v[90:93], v[188:191], v[248:251], v[90:93]
	v_mfma_f32_16x16x32_bf16 v[86:89], v[216:219], v[240:243], v[86:89]
	v_mfma_f32_16x16x32_bf16 v[82:85], v[216:219], v[248:251], v[82:85]
	v_mfma_f32_16x16x32_bf16 v[78:81], v[224:227], v[240:243], v[78:81]
	v_mfma_f32_16x16x32_bf16 v[74:77], v[224:227], v[248:251], v[74:77]
	v_mfma_f32_16x16x32_bf16 v[70:73], v[232:235], v[240:243], v[70:73]
	v_mfma_f32_16x16x32_bf16 v[66:69], v[232:235], v[248:251], v[66:69]
	s_setprio 0
	v_readfirstlane_b32 s5, v158
	v_lshl_add_u64 v[184:185], v[184:185], 0, s[70:71]
	s_mov_b32 m0, s5
	v_readfirstlane_b32 s5, v159
	s_barrier
; #define STAGE_A(Pp, br, kt) { const char* g_ = (const char*)(A + (size_t)(br) * lda + (size_t)(kt) * BK); \
;     __builtin_amdgcn_global_load_lds((const unsigned*)(g_ + oa0), (LAS unsigned*)((Pp) + tid * 16), 16, 0, 0); \
;     __builtin_amdgcn_global_load_lds((const unsigned*)(g_ + oa1), (LAS unsigned*)((Pp) + tid * 16 + 8192), 16, 0, 0); }
; #define STAGE_B(Pp, br, kt) { const char* g_ = (const char*)(Bt + (size_t)(br) * ldb + (size_t)(kt) * BK); \
;     __builtin_amdgcn_global_load_lds((const unsigned*)(g_ + ob0), (LAS unsigned*)((Pp) + tid * 16), 16, 0, 0); \
;     __builtin_amdgcn_global_load_lds((const unsigned*)(g_ + ob1), (LAS unsigned*)((Pp) + tid * 16 + 8192), 16, 0, 0); }
; #define LDA8(dst, b, h) _Pragma("unroll") for (int m = 0; m < 4; ++m) _Pragma("unroll") for (int k = 0; k < 2; ++k) \
;     dst[m][k] = *(const bf16x8*)(lrda + ((b) * 2 + (h)) * HTB + (2 * m + k) * 1024)
; #define LDB8(dst, b, h) _Pragma("unroll") for (int n = 0; n < 2; ++n) _Pragma("unroll") for (int k = 0; k < 2; ++k) \
;     dst[n][k] = *(const bf16x8*)(lrdb + ((b) * 2 + (h)) * HTB + (2 * n + k) * 1024)
; #define MMA8(ai, bj, AT, BT) { __builtin_amdgcn_s_setprio(1); \
;     _Pragma("unroll") for (int m = 0; m < 4; ++m) _Pragma("unroll") for (int n = 0; n < 2; ++n) _Pragma("unroll") for (int k = 0; k < 2; ++k) \
;       acc[ai][bj][m][n] = __builtin_amdgcn_mfma_f32_16x16x32_bf16(AT[m][k], BT[n][k], acc[ai][bj][m][n], 0, 0, 0); \
;     __builtin_amdgcn_s_setprio(0); }
; #define WAIT_V(n) asm volatile("s_waitcnt vmcnt(" #n ")" ::: "memory")
; #define WAIT_L(n) asm volatile("s_waitcnt lgkmcnt(" #n ")" ::: "memory")
; #define BAR8 __builtin_amdgcn_s_barrier()
; #define SCHED8 __builtin_amdgcn_sched_barrier(0)
; template <class Epi>
; DI void gemm256(const bf16_t* __restrict__ A, int lda, const bf16_t* __restrict__ Bt, int ldb, int K, char* lds, Epi epi) {
;     ...
;     LDA8(At, 1, 1); STAGE_A(SA8(1, 0), 0, t + 3);
;     BAR8; WAIT_L(0); MMA8(1, 0, At, B0); BAR8; SCHED8;
;     STAGE_B(SB8(1, 1), HALFR, t + 3);
;     WAIT_V(6); BAR8; MMA8(1, 1, At, B1); BAR8;
;   }
;   { LDB8(B0, 0, 0); LDA8(At, 0, 0); STAGE_A(SA8(1, 1), HALFR, nt - 1);
;     BAR8; WAIT_L(0); MMA8(0, 0, At, B0); BAR8;
	ds_read_b128 v[180:183], v146 offset:49152
	ds_read_b128 v[188:191], v146 offset:50176
	ds_read_b128 v[192:195], v146 offset:51200
	ds_read_b128 v[216:219], v146 offset:52224
	ds_read_b128 v[220:223], v146 offset:53248
	ds_read_b128 v[224:227], v146 offset:54272
	ds_read_b128 v[228:231], v146 offset:55296
	ds_read_b128 v[232:235], v146 offset:56320
	global_load_lds_dwordx4 v[184:185], off
	v_lshl_add_u64 v[184:185], v[202:203], 0, s[70:71]
	s_mov_b32 m0, s5
	s_nop 0
	global_load_lds_dwordx4 v[184:185], off
	s_barrier
	s_waitcnt lgkmcnt(0)
	s_setprio 1
	s_waitcnt lgkmcnt(0)
	v_mfma_f32_16x16x32_bf16 v[62:65], v[180:183], v[164:167], v[62:65]
	v_mfma_f32_16x16x32_bf16 v[58:61], v[180:183], v[172:175], v[58:61]
	v_mfma_f32_16x16x32_bf16 v[54:57], v[192:195], v[164:167], v[54:57]
	v_mfma_f32_16x16x32_bf16 v[50:53], v[192:195], v[172:175], v[50:53]
	v_mfma_f32_16x16x32_bf16 v[46:49], v[220:223], v[164:167], v[46:49]
	v_mfma_f32_16x16x32_bf16 v[42:45], v[220:223], v[172:175], v[42:45]
	v_mfma_f32_16x16x32_bf16 v[38:41], v[228:231], v[164:167], v[38:41]
	v_mfma_f32_16x16x32_bf16 v[34:37], v[228:231], v[172:175], v[34:37]
	v_mfma_f32_16x16x32_bf16 v[62:65], v[188:191], v[168:171], v[62:65]
	v_mfma_f32_16x16x32_bf16 v[58:61], v[188:191], v[176:179], v[58:61]
	v_mfma_f32_16x16x32_bf16 v[54:57], v[216:219], v[168:171], v[54:57]
	v_mfma_f32_16x16x32_bf16 v[50:53], v[216:219], v[176:179], v[50:53]
	v_mfma_f32_16x16x32_bf16 v[46:49], v[224:227], v[168:171], v[46:49]
	v_mfma_f32_16x16x32_bf16 v[42:45], v[224:227], v[176:179], v[42:45]
	v_mfma_f32_16x16x32_bf16 v[38:41], v[232:235], v[168:171], v[38:41]
	v_mfma_f32_16x16x32_bf16 v[34:37], v[232:235], v[176:179], v[34:37]
	s_setprio 0
	s_barrier
	v_readfirstlane_b32 s5, v160
	v_lshl_add_u64 v[164:165], v[210:211], 0, s[98:99]
	s_mov_b32 m0, s5
	v_readfirstlane_b32 s5, v161
	global_load_lds_dwordx4 v[164:165], off
	v_lshl_add_u64 v[164:165], v[212:213], 0, s[98:99]
	s_mov_b32 m0, s5
	s_nop 0
	global_load_lds_dwordx4 v[164:165], off
	s_waitcnt vmcnt(10)
	s_barrier
	s_setprio 1
	v_mfma_f32_16x16x32_bf16 v[30:33], v[180:183], v[236:239], v[30:33]
	v_mfma_f32_16x16x32_bf16 v[26:29], v[180:183], v[244:247], v[26:29]
	v_mfma_f32_16x16x32_bf16 v[22:25], v[192:195], v[236:239], v[22:25]
	v_mfma_f32_16x16x32_bf16 v[18:21], v[192:195], v[244:247], v[18:21]
	v_mfma_f32_16x16x32_bf16 v[14:17], v[220:223], v[236:239], v[14:17]
	v_mfma_f32_16x16x32_bf16 v[10:13], v[220:223], v[244:247], v[10:13]
	v_mfma_f32_16x16x32_bf16 v[6:9], v[228:231], v[236:239], v[6:9]
	v_mfma_f32_16x16x32_bf16 v[2:5], v[228:231], v[244:247], v[2:5]
	v_mfma_f32_16x16x32_bf16 v[30:33], v[188:191], v[240:243], v[30:33]
	v_mfma_f32_16x16x32_bf16 v[26:29], v[188:191], v[248:251], v[26:29]
	v_mfma_f32_16x16x32_bf16 v[22:25], v[216:219], v[240:243], v[22:25]
	v_mfma_f32_16x16x32_bf16 v[18:21], v[216:219], v[248:251], v[18:21]
	v_mfma_f32_16x16x32_bf16 v[14:17], v[224:227], v[240:243], v[14:17]
	v_mfma_f32_16x16x32_bf16 v[10:13], v[224:227], v[248:251], v[10:13]
	v_mfma_f32_16x16x32_bf16 v[6:9], v[232:235], v[240:243], v[6:9]
	v_mfma_f32_16x16x32_bf16 v[2:5], v[232:235], v[248:251], v[2:5]
	s_setprio 0
	s_add_i32 s2, s2, 2
	v_lshl_add_u64 v[132:133], v[132:133], 0, s[22:23]
	v_lshl_add_u64 v[134:135], v[134:135], 0, s[22:23]
	v_lshl_add_u64 v[136:137], v[136:137], 0, s[22:23]
	s_cmp_lt_u32 s2, 12
	v_lshl_add_u64 v[138:139], v[138:139], 0, s[22:23]
	s_barrier
	s_cbranch_scc1 .LBB0_346
	s_add_u32 s18, s48, 0x40780
	s_addc_u32 s19, s49, 0
	v_readfirstlane_b32 s2, v162
	v_lshl_add_u64 v[160:161], s[18:19], 0, v[0:1]
	s_mov_b32 m0, s2
	v_readfirstlane_b32 s2, v163
	ds_read_b128 v[132:135], v147
	ds_read_b128 v[136:139], v147 offset:1024
	ds_read_b128 v[148:151], v147 offset:2048
	ds_read_b128 v[152:155], v147 offset:3072
	ds_read_b128 v[156:159], v146
	ds_read_b128 v[164:167], v146 offset:1024
	ds_read_b128 v[168:171], v146 offset:2048
	ds_read_b128 v[172:175], v146 offset:3072
	ds_read_b128 v[176:179], v146 offset:4096
	ds_read_b128 v[180:183], v146 offset:5120
	ds_read_b128 v[188:191], v146 offset:6144
	ds_read_b128 v[192:195], v146 offset:7168
	global_load_lds_dwordx4 v[160:161], off
	v_lshl_add_u64 v[130:131], s[18:19], 0, v[130:131]
	s_mov_b32 m0, s2
	s_nop 0
	global_load_lds_dwordx4 v[130:131], off
	s_waitcnt vmcnt(10)
	s_barrier
	s_waitcnt lgkmcnt(0)
	s_setprio 1
	s_waitcnt lgkmcnt(0)
	v_mfma_f32_16x16x32_bf16 v[126:129], v[156:159], v[132:135], v[126:129]
	v_mfma_f32_16x16x32_bf16 v[122:125], v[156:159], v[148:151], v[122:125]
	v_mfma_f32_16x16x32_bf16 v[118:121], v[168:171], v[132:135], v[118:121]
	v_mfma_f32_16x16x32_bf16 v[110:113], v[176:179], v[132:135], v[110:113]
	v_mfma_f32_16x16x32_bf16 v[106:109], v[176:179], v[148:151], v[106:109]
	v_mfma_f32_16x16x32_bf16 v[102:105], v[188:191], v[132:135], v[102:105]
	v_mfma_f32_16x16x32_bf16 v[98:101], v[188:191], v[148:151], v[98:101]
	v_mfma_f32_16x16x32_bf16 v[126:129], v[164:167], v[136:139], v[126:129]
	v_mfma_f32_16x16x32_bf16 v[122:125], v[164:167], v[152:155], v[122:125]
	v_mfma_f32_16x16x32_bf16 v[118:121], v[172:175], v[136:139], v[118:121]
	v_mfma_f32_16x16x32_bf16 v[114:117], v[168:171], v[148:151], v[114:117]
	v_mfma_f32_16x16x32_bf16 v[110:113], v[180:183], v[136:139], v[110:113]
	v_mfma_f32_16x16x32_bf16 v[106:109], v[180:183], v[152:155], v[106:109]
	v_mfma_f32_16x16x32_bf16 v[102:105], v[192:195], v[136:139], v[102:105]
	v_mfma_f32_16x16x32_bf16 v[98:101], v[192:195], v[152:155], v[98:101]
	v_mfma_f32_16x16x32_bf16 v[160:163], v[172:175], v[152:155], v[114:117]
	s_setprio 0
	s_barrier
; #define LDA8(dst, b, h) _Pragma("unroll") for (int m = 0; m < 4; ++m) _Pragma("unroll") for (int k = 0; k < 2; ++k) \
;     dst[m][k] = *(const bf16x8*)(lrda + ((b) * 2 + (h)) * HTB + (2 * m + k) * 1024)
; #define LDB8(dst, b, h) _Pragma("unroll") for (int n = 0; n < 2; ++n) _Pragma("unroll") for (int k = 0; k < 2; ++k) \
;     dst[n][k] = *(const bf16x8*)(lrdb + ((b) * 2 + (h)) * HTB + (2 * n + k) * 1024)
; #define MMA8(ai, bj, AT, BT) { __builtin_amdgcn_s_setprio(1); \
;     _Pragma("unroll") for (int m = 0; m < 4; ++m) _Pragma("unroll") for (int n = 0; n < 2; ++n) _Pragma("unroll") for (int k = 0; k < 2; ++k) \
;       acc[ai][bj][m][n] = __builtin_amdgcn_mfma_f32_16x16x32_bf16(AT[m][k], BT[n][k], acc[ai][bj][m][n], 0, 0, 0); \
;     __builtin_amdgcn_s_setprio(0); }
; #define WAIT_V(n) asm volatile("s_waitcnt vmcnt(" #n ")" ::: "memory")
; #define WAIT_L(n) asm volatile("s_waitcnt lgkmcnt(" #n ")" ::: "memory")
; #define BAR8 __builtin_amdgcn_s_barrier()
; template <class Epi>
; DI void gemm256(const bf16_t* __restrict__ A, int lda, const bf16_t* __restrict__ Bt, int ldb, int K, char* lds, Epi epi) {
;     ...
;     LDB8(B1, 0, 1); BAR8; WAIT_L(0); MMA8(0, 1, At, B1); BAR8;
;     LDA8(At, 0, 1); WAIT_V(4); BAR8; WAIT_L(0); MMA8(1, 0, At, B0); MMA8(1, 1, At, B1); BAR8; }
;   { LDB8(B0, 1, 0); LDA8(At, 1, 0); WAIT_V(2); BAR8; WAIT_L(0); MMA8(0, 0, At, B0); BAR8;
	s_nop 0
	ds_read_b128 v[114:117], v147 offset:16384
	ds_read_b128 v[216:219], v147 offset:17408
	ds_read_b128 v[220:223], v147 offset:18432
	ds_read_b128 v[224:227], v147 offset:19456
	s_waitcnt vmcnt(8)
	s_barrier
	s_waitcnt lgkmcnt(0)
	s_setprio 1
	s_waitcnt lgkmcnt(0)
	v_mfma_f32_16x16x32_bf16 v[90:93], v[156:159], v[220:223], v[90:93]
	v_mfma_f32_16x16x32_bf16 v[86:89], v[168:171], v[114:117], v[86:89]
	v_mfma_f32_16x16x32_bf16 v[94:97], v[156:159], v[114:117], v[94:97]
	v_mfma_f32_16x16x32_bf16 v[90:93], v[164:167], v[224:227], v[90:93]
	v_mfma_f32_16x16x32_bf16 v[86:89], v[172:175], v[216:219], v[86:89]
	v_mfma_f32_16x16x32_bf16 v[82:85], v[168:171], v[220:223], v[82:85]
	v_mfma_f32_16x16x32_bf16 v[78:81], v[176:179], v[114:117], v[78:81]
	v_mfma_f32_16x16x32_bf16 v[74:77], v[176:179], v[220:223], v[74:77]
	v_mfma_f32_16x16x32_bf16 v[70:73], v[188:191], v[114:117], v[70:73]
	v_mfma_f32_16x16x32_bf16 v[66:69], v[188:191], v[220:223], v[66:69]
	v_mfma_f32_16x16x32_bf16 v[228:231], v[164:167], v[216:219], v[94:97]
	v_mfma_f32_16x16x32_bf16 v[156:159], v[172:175], v[224:227], v[82:85]
	v_mfma_f32_16x16x32_bf16 v[164:167], v[180:183], v[216:219], v[78:81]
	v_mfma_f32_16x16x32_bf16 v[168:171], v[180:183], v[224:227], v[74:77]
	v_mfma_f32_16x16x32_bf16 v[172:175], v[192:195], v[216:219], v[70:73]
	v_mfma_f32_16x16x32_bf16 v[176:179], v[192:195], v[224:227], v[66:69]
	s_setprio 0
	s_barrier
	s_nop 0
	ds_read_b128 v[66:69], v146 offset:16384
	ds_read_b128 v[70:73], v146 offset:17408
	ds_read_b128 v[74:77], v146 offset:18432
	ds_read_b128 v[78:81], v146 offset:19456
	ds_read_b128 v[82:85], v146 offset:20480
	ds_read_b128 v[94:97], v146 offset:21504
	ds_read_b128 v[180:183], v146 offset:22528
	ds_read_b128 v[188:191], v146 offset:23552
	s_waitcnt vmcnt(4)
	s_barrier
	s_waitcnt lgkmcnt(0)
	s_setprio 1
	s_waitcnt lgkmcnt(0)
	v_mfma_f32_16x16x32_bf16 v[62:65], v[66:69], v[132:135], v[62:65]
	v_mfma_f32_16x16x32_bf16 v[58:61], v[66:69], v[148:151], v[58:61]
	v_mfma_f32_16x16x32_bf16 v[54:57], v[74:77], v[132:135], v[54:57]
	v_mfma_f32_16x16x32_bf16 v[50:53], v[74:77], v[148:151], v[50:53]
	v_mfma_f32_16x16x32_bf16 v[46:49], v[82:85], v[132:135], v[46:49]
	v_mfma_f32_16x16x32_bf16 v[42:45], v[82:85], v[148:151], v[42:45]
	v_mfma_f32_16x16x32_bf16 v[38:41], v[180:183], v[132:135], v[38:41]
	v_mfma_f32_16x16x32_bf16 v[34:37], v[180:183], v[148:151], v[34:37]
	v_mfma_f32_16x16x32_bf16 v[62:65], v[70:73], v[136:139], v[62:65]
	v_mfma_f32_16x16x32_bf16 v[58:61], v[70:73], v[152:155], v[58:61]
	v_mfma_f32_16x16x32_bf16 v[54:57], v[78:81], v[136:139], v[54:57]
	v_mfma_f32_16x16x32_bf16 v[50:53], v[78:81], v[152:155], v[50:53]
	v_mfma_f32_16x16x32_bf16 v[46:49], v[94:97], v[136:139], v[46:49]
	v_mfma_f32_16x16x32_bf16 v[42:45], v[94:97], v[152:155], v[42:45]
	v_mfma_f32_16x16x32_bf16 v[38:41], v[188:191], v[136:139], v[38:41]
	v_mfma_f32_16x16x32_bf16 v[34:37], v[188:191], v[152:155], v[34:37]
	s_setprio 0
	s_setprio 1
	v_mfma_f32_16x16x32_bf16 v[30:33], v[66:69], v[114:117], v[30:33]
	v_mfma_f32_16x16x32_bf16 v[26:29], v[66:69], v[220:223], v[26:29]
	v_mfma_f32_16x16x32_bf16 v[22:25], v[74:77], v[114:117], v[22:25]
	v_mfma_f32_16x16x32_bf16 v[18:21], v[74:77], v[220:223], v[18:21]
	v_mfma_f32_16x16x32_bf16 v[14:17], v[82:85], v[114:117], v[14:17]
	v_mfma_f32_16x16x32_bf16 v[10:13], v[82:85], v[220:223], v[10:13]
	v_mfma_f32_16x16x32_bf16 v[6:9], v[180:183], v[114:117], v[6:9]
	v_mfma_f32_16x16x32_bf16 v[2:5], v[180:183], v[220:223], v[2:5]
	v_mfma_f32_16x16x32_bf16 v[130:133], v[70:73], v[216:219], v[30:33]
	v_mfma_f32_16x16x32_bf16 v[134:137], v[70:73], v[224:227], v[26:29]
	v_mfma_f32_16x16x32_bf16 v[148:151], v[78:81], v[216:219], v[22:25]
	v_mfma_f32_16x16x32_bf16 v[152:155], v[78:81], v[224:227], v[18:21]
	v_mfma_f32_16x16x32_bf16 v[192:195], v[94:97], v[216:219], v[14:17]
	v_mfma_f32_16x16x32_bf16 v[232:235], v[94:97], v[224:227], v[10:13]
	v_mfma_f32_16x16x32_bf16 v[216:219], v[188:191], v[216:219], v[6:9]
	v_mfma_f32_16x16x32_bf16 v[180:183], v[188:191], v[224:227], v[2:5]
	s_setprio 0
	s_barrier
	ds_read_b128 v[14:17], v147 offset:32768
	ds_read_b128 v[30:33], v147 offset:33792
	ds_read_b128 v[188:191], v147 offset:34816
	ds_read_b128 v[220:223], v147 offset:35840
	ds_read_b128 v[2:5], v146 offset:32768
	ds_read_b128 v[6:9], v146 offset:33792
	ds_read_b128 v[10:13], v146 offset:34816
	ds_read_b128 v[18:21], v146 offset:35840
	ds_read_b128 v[22:25], v146 offset:36864
	ds_read_b128 v[26:29], v146 offset:37888
	ds_read_b128 v[224:227], v146 offset:38912
	ds_read_b128 v[236:239], v146 offset:39936
	s_waitcnt vmcnt(2)
	s_barrier
; #define LDA8(dst, b, h) _Pragma("unroll") for (int m = 0; m < 4; ++m) _Pragma("unroll") for (int k = 0; k < 2; ++k) \
;     dst[m][k] = *(const bf16x8*)(lrda + ((b) * 2 + (h)) * HTB + (2 * m + k) * 1024)
; #define LDB8(dst, b, h) _Pragma("unroll") for (int n = 0; n < 2; ++n) _Pragma("unroll") for (int k = 0; k < 2; ++k) \
;     dst[n][k] = *(const bf16x8*)(lrdb + ((b) * 2 + (h)) * HTB + (2 * n + k) * 1024)
; #define MMA8(ai, bj, AT, BT) { __builtin_amdgcn_s_setprio(1); \
;     _Pragma("unroll") for (int m = 0; m < 4; ++m) _Pragma("unroll") for (int n = 0; n < 2; ++n) _Pragma("unroll") for (int k = 0; k < 2; ++k) \
;       acc[ai][bj][m][n] = __builtin_amdgcn_mfma_f32_16x16x32_bf16(AT[m][k], BT[n][k], acc[ai][bj][m][n], 0, 0, 0); \
;     __builtin_amdgcn_s_setprio(0); }
; #define WAIT_V(n) asm volatile("s_waitcnt vmcnt(" #n ")" ::: "memory")
; #define WAIT_L(n) asm volatile("s_waitcnt lgkmcnt(" #n ")" ::: "memory")
; #define BAR8 __builtin_amdgcn_s_barrier()
; template <class Epi>
; DI void gemm256(const bf16_t* __restrict__ A, int lda, const bf16_t* __restrict__ Bt, int ldb, int K, char* lds, Epi epi) {
;     ...
;   { LDB8(B0, 1, 0); LDA8(At, 1, 0); WAIT_V(2); BAR8; WAIT_L(0); MMA8(0, 0, At, B0); BAR8;
;     LDB8(B1, 1, 1); WAIT_V(0); BAR8; WAIT_L(0); MMA8(0, 1, At, B1); BAR8;
;     LDA8(At, 1, 1); BAR8; WAIT_L(0); MMA8(1, 0, At, B0); MMA8(1, 1, At, B1); BAR8; }
;   if (wr == 0) BAR8;
	s_waitcnt lgkmcnt(0)
	s_setprio 1
	s_waitcnt lgkmcnt(0)
	v_mfma_f32_16x16x32_bf16 v[66:69], v[2:5], v[14:17], v[126:129]
	v_mfma_f32_16x16x32_bf16 v[114:117], v[6:9], v[30:33], v[66:69]
	v_mfma_f32_16x16x32_bf16 v[66:69], v[2:5], v[188:191], v[122:125]
	v_mfma_f32_16x16x32_bf16 v[126:129], v[6:9], v[220:223], v[66:69]
	v_mfma_f32_16x16x32_bf16 v[66:69], v[10:13], v[14:17], v[118:121]
	v_mfma_f32_16x16x32_bf16 v[82:85], v[18:21], v[30:33], v[66:69]
	v_mfma_f32_16x16x32_bf16 v[66:69], v[10:13], v[188:191], v[160:163]
	v_mfma_f32_16x16x32_bf16 v[94:97], v[18:21], v[220:223], v[66:69]
	v_mfma_f32_16x16x32_bf16 v[66:69], v[22:25], v[14:17], v[110:113]
	v_mfma_f32_16x16x32_bf16 v[74:77], v[26:29], v[30:33], v[66:69]
	v_mfma_f32_16x16x32_bf16 v[66:69], v[22:25], v[188:191], v[106:109]
	v_mfma_f32_16x16x32_bf16 v[78:81], v[26:29], v[220:223], v[66:69]
	v_mfma_f32_16x16x32_bf16 v[66:69], v[224:227], v[14:17], v[102:105]
	v_mfma_f32_16x16x32_bf16 v[70:73], v[224:227], v[188:191], v[98:101]
	v_mfma_f32_16x16x32_bf16 v[66:69], v[236:239], v[30:33], v[66:69]
	v_mfma_f32_16x16x32_bf16 v[70:73], v[236:239], v[220:223], v[70:73]
	s_setprio 0
	s_barrier
	ds_read_b128 v[160:163], v147 offset:49152
	ds_read_b128 v[240:243], v147 offset:50176
	ds_read_b128 v[244:247], v147 offset:51200
	ds_read_b128 v[248:251], v147 offset:52224
	s_waitcnt vmcnt(0)
	s_barrier
	s_waitcnt lgkmcnt(0)
	s_setprio 1
	s_waitcnt lgkmcnt(0)
	v_mfma_f32_16x16x32_bf16 v[98:101], v[2:5], v[160:163], v[228:231]
	v_mfma_f32_16x16x32_bf16 v[2:5], v[2:5], v[244:247], v[90:93]
	v_mfma_f32_16x16x32_bf16 v[118:121], v[6:9], v[248:251], v[2:5]
	v_mfma_f32_16x16x32_bf16 v[2:5], v[10:13], v[160:163], v[86:89]
	v_mfma_f32_16x16x32_bf16 v[102:105], v[18:21], v[240:243], v[2:5]
	v_mfma_f32_16x16x32_bf16 v[2:5], v[10:13], v[244:247], v[156:159]
	v_mfma_f32_16x16x32_bf16 v[122:125], v[18:21], v[248:251], v[2:5]
	v_mfma_f32_16x16x32_bf16 v[2:5], v[22:25], v[160:163], v[164:167]
	v_mfma_f32_16x16x32_bf16 v[90:93], v[26:29], v[240:243], v[2:5]
	v_mfma_f32_16x16x32_bf16 v[2:5], v[22:25], v[244:247], v[168:171]
	v_mfma_f32_16x16x32_bf16 v[110:113], v[26:29], v[248:251], v[2:5]
	v_mfma_f32_16x16x32_bf16 v[2:5], v[224:227], v[160:163], v[172:175]
	v_mfma_f32_16x16x32_bf16 v[86:89], v[236:239], v[240:243], v[2:5]
	v_mfma_f32_16x16x32_bf16 v[2:5], v[224:227], v[244:247], v[176:179]
	v_mfma_f32_16x16x32_bf16 v[98:101], v[6:9], v[240:243], v[98:101]
	v_mfma_f32_16x16x32_bf16 v[106:109], v[236:239], v[248:251], v[2:5]
	s_setprio 0
	s_barrier
	ds_read_b128 v[156:159], v146 offset:49152
	ds_read_b128 v[164:167], v146 offset:50176
	ds_read_b128 v[168:171], v146 offset:51200
	ds_read_b128 v[172:175], v146 offset:52224
	ds_read_b128 v[176:179], v146 offset:53248
	ds_read_b128 v[224:227], v146 offset:54272
	ds_read_b128 v[228:231], v146 offset:55296
	ds_read_b128 v[236:239], v146 offset:56320
	s_barrier
	s_waitcnt lgkmcnt(0)
	s_setprio 1
	s_waitcnt lgkmcnt(0)
	v_mfma_f32_16x16x32_bf16 v[6:9], v[156:159], v[188:191], v[58:61]
	v_mfma_f32_16x16x32_bf16 v[10:13], v[168:171], v[188:191], v[50:53]
	v_mfma_f32_16x16x32_bf16 v[2:5], v[156:159], v[14:17], v[62:65]
	v_mfma_f32_16x16x32_bf16 v[18:21], v[164:167], v[220:223], v[6:9]
	v_mfma_f32_16x16x32_bf16 v[6:9], v[168:171], v[14:17], v[54:57]
	v_mfma_f32_16x16x32_bf16 v[22:25], v[172:175], v[220:223], v[10:13]
	v_mfma_f32_16x16x32_bf16 v[10:13], v[176:179], v[14:17], v[46:49]
	v_mfma_f32_16x16x32_bf16 v[14:17], v[228:231], v[14:17], v[38:41]
	v_mfma_f32_16x16x32_bf16 v[2:5], v[164:167], v[30:33], v[2:5]
	v_mfma_f32_16x16x32_bf16 v[6:9], v[172:175], v[30:33], v[6:9]
	v_mfma_f32_16x16x32_bf16 v[10:13], v[224:227], v[30:33], v[10:13]
	v_mfma_f32_16x16x32_bf16 v[26:29], v[176:179], v[188:191], v[42:45]
	v_mfma_f32_16x16x32_bf16 v[14:17], v[236:239], v[30:33], v[14:17]
	v_mfma_f32_16x16x32_bf16 v[30:33], v[228:231], v[188:191], v[34:37]
	v_mfma_f32_16x16x32_bf16 v[26:29], v[224:227], v[220:223], v[26:29]
	v_mfma_f32_16x16x32_bf16 v[30:33], v[236:239], v[220:223], v[30:33]
	s_setprio 0
	s_setprio 1
	v_mfma_f32_16x16x32_bf16 v[38:41], v[156:159], v[244:247], v[134:137]
	v_mfma_f32_16x16x32_bf16 v[42:45], v[168:171], v[244:247], v[152:155]
	v_mfma_f32_16x16x32_bf16 v[46:49], v[176:179], v[244:247], v[232:235]
	v_mfma_f32_16x16x32_bf16 v[34:37], v[156:159], v[160:163], v[130:133]
	v_mfma_f32_16x16x32_bf16 v[50:53], v[164:167], v[248:251], v[38:41]
	v_mfma_f32_16x16x32_bf16 v[38:41], v[168:171], v[160:163], v[148:151]
	v_mfma_f32_16x16x32_bf16 v[54:57], v[172:175], v[248:251], v[42:45]
	v_mfma_f32_16x16x32_bf16 v[42:45], v[176:179], v[160:163], v[192:195]
	v_mfma_f32_16x16x32_bf16 v[58:61], v[224:227], v[248:251], v[46:49]
	v_mfma_f32_16x16x32_bf16 v[46:49], v[228:231], v[160:163], v[216:219]
	v_mfma_f32_16x16x32_bf16 v[62:65], v[228:231], v[244:247], v[180:183]
	v_mfma_f32_16x16x32_bf16 v[34:37], v[164:167], v[240:243], v[34:37]
	v_mfma_f32_16x16x32_bf16 v[38:41], v[172:175], v[240:243], v[38:41]
	v_mfma_f32_16x16x32_bf16 v[42:45], v[224:227], v[240:243], v[42:45]
	v_mfma_f32_16x16x32_bf16 v[46:49], v[236:239], v[240:243], v[46:49]
	v_mfma_f32_16x16x32_bf16 v[62:65], v[236:239], v[248:251], v[62:65]
	s_setprio 0
	s_movk_i32 s2, 0x100
	v_cmp_gt_u32_e32 vcc, s2, v140
	s_barrier
	s_and_saveexec_b64 s[18:19], vcc
	s_mov_b64 s[72:73], 0x1000
	s_cbranch_execz .LBB0_349
	s_barrier
